# first K-iteration peeled in 5 main GEMM loops: accumulators initialised by a srcC=0 MFMA, the 62 v_mov_b64 zeroing copies per unit removed from the unit-boundary critical path; on top of v74
# speedup vs baseline: 1.0067x; 1.0008x over previous
; #define PG8_STAGEX(rs, bufoff, soff, voff) do { _Pragma("unroll") for (int _i = 0; _i < 2; ++_i) \
;         __builtin_amdgcn_raw_ptr_buffer_load_lds(rs, (LAS unsigned*)(lds + (bufoff) + ldsw + _i * 8192), 16, (voff)[_i], (soff), 0, 0); } while (0)
; #define PG8_LDA(dst, b, h) do { _Pragma("unroll") for (int m = 0; m < 4; ++m) _Pragma("unroll") for (int k = 0; k < 2; ++k) dst[m][k] = *(const LAS bf16x8*)(lds + PG8_SA(b, h) + aoff + m * 2048 + k * 1024); } while (0)
; #define PG8_LDB(dst, b, h) do { _Pragma("unroll") for (int n = 0; n < 2; ++n) _Pragma("unroll") for (int k = 0; k < 2; ++k) dst[n][k] = *(const LAS bf16x8*)(lds + PG8_SB(b, h) + boff + n * 2048 + k * 1024); } while (0)
; #define PG8_WAIT_V(n) asm volatile("s_waitcnt vmcnt(" #n ")" ::: "memory")
; #define PG8_WAIT_L(n) asm volatile("s_waitcnt lgkmcnt(" #n ")" ::: "memory")
; #define PG8_BAR __builtin_amdgcn_s_barrier()
; #define PG8_SCHED __builtin_amdgcn_sched_barrier(0)
;     ...
;             PG8_LDB(B0, 0, 0); PG8_LDB(B1, 0, 1); PG8_SCHED; PG8_LDA(At, 0, 0); PG8_STAGEX(rsA, PG8_SA(1, 1), a1 + hstepA, voffA);
;             PG8_WAIT_V(8); PG8_WAIT_L(0); PG8_BAR; PG8_MMA(0, 0, At, B0); PG8_MMA(0, 1, At, B1); PG8_BAR; PG8_SCHED;
;             PG8_LDA(At, 0, 1); PG8_STAGEX(rsB, PG8_SB(0, 0), b2, voffB); PG8_STAGEX(rsB, PG8_SB(0, 1), b2 + hstepB, voffB); PG8_STAGEX(rsA, PG8_SA(0, 0), a2, voffA);
;             PG8_WAIT_V(8); PG8_WAIT_L(0); PG8_BAR; PG8_MMA(1, 0, At, B0); PG8_MMA(1, 1, At, B1); PG8_BAR; PG8_SCHED;
;     ...
;         if (!cur.keep) {
; #pragma unroll
;             for (int a = 0; a < 2; ++a)
; #pragma unroll
;                 for (int b = 0; b < 2; ++b)
; #pragma unroll
;                     for (int m = 0; m < 4; ++m)
; #pragma unroll
;                         for (int n = 0; n < 2; ++n) { f32x2 z0, z1; asm("v_mov_b64 %0, 0\n\tv_mov_b64 %1, 0" : "=v"(z0), "=v"(z1));
;                     acc[a][b][m][n] = __builtin_shufflevector(z0, z1, 0, 1, 2, 3); }
.LBB0_222:
	s_lshl_b32 s28, s27, 20
	s_and_b64 s[30:31], s[38:39], exec
	s_cselect_b32 s30, s28, s50
	s_lshl_b32 s29, s26, 20
	s_and_b64 s[52:53], s[38:39], exec
	s_waitcnt vmcnt(15)
	s_cselect_b32 s31, s29, s42
	s_add_i32 s50, s50, 0x80080
	s_add_i32 s51, s42, 0x100
	s_mov_b32 s52, -2
	v_add_u32_e32 v102, 0x10000, v172
	v_add_u32_e32 v146, 0x14000, v172
	ds_read_b128 v[82:85], v102
	ds_read_b128 v[86:89], v102 offset:1024
	ds_read_b128 v[98:101], v102 offset:2048
	ds_read_b128 v[102:105], v102 offset:3072
	ds_read_b128 v[150:153], v146
	ds_read_b128 v[154:157], v146 offset:1024
	ds_read_b128 v[182:185], v146 offset:2048
	ds_read_b128 v[186:189], v146 offset:3072
	s_add_i32 s42, s50, 0xfff80080
	s_cmp_eq_u32 s52, 28
	s_cselect_b32 s55, s30, s42
	s_cselect_b32 s54, s31, s51
	s_or_b32 s53, s55, 0x80
	s_mov_b32 m0, s22
	ds_read_b128 v[190:193], v173
	ds_read_b128 v[194:197], v173 offset:1024
	ds_read_b128 v[198:201], v173 offset:2048
	ds_read_b128 v[202:205], v173 offset:3072
	ds_read_b128 v[206:209], v173 offset:4096
	ds_read_b128 v[210:213], v173 offset:5120
	ds_read_b128 v[214:217], v173 offset:6144
	ds_read_b128 v[218:221], v173 offset:7168
	buffer_load_dwordx4 v159, s[76:79], s50 offen lds
	s_mov_b32 m0, s23
	s_nop 0
	buffer_load_dwordx4 v163, s[76:79], s50 offen lds
	s_waitcnt vmcnt(8)
	s_waitcnt lgkmcnt(0)
	s_setprio 1
	s_barrier
	v_mfma_f32_16x16x32_bf16 v[142:145], v[82:85], v[190:193], 0
	v_mfma_f32_16x16x32_bf16 v[142:145], v[86:89], v[194:197], v[142:145]
	v_mfma_f32_16x16x32_bf16 v[134:137], v[102:105], v[194:197], 0
	v_mfma_f32_16x16x32_bf16 v[134:137], v[98:101], v[190:193], v[134:137]
	v_mfma_f32_16x16x32_bf16 v[118:121], v[98:101], v[198:201], 0
	v_mfma_f32_16x16x32_bf16 v[118:121], v[102:105], v[202:205], v[118:121]
	v_mfma_f32_16x16x32_bf16 v[126:129], v[86:89], v[202:205], 0
	v_mfma_f32_16x16x32_bf16 v[126:129], v[82:85], v[198:201], v[126:129]
	v_mfma_f32_16x16x32_bf16 v[110:113], v[82:85], v[206:209], 0
	v_mfma_f32_16x16x32_bf16 v[110:113], v[86:89], v[210:213], v[110:113]
	v_mfma_f32_16x16x32_bf16 v[94:97], v[102:105], v[210:213], 0
	v_mfma_f32_16x16x32_bf16 v[94:97], v[98:101], v[206:209], v[94:97]
	v_mfma_f32_16x16x32_bf16 v[70:73], v[98:101], v[214:217], 0
	v_mfma_f32_16x16x32_bf16 v[70:73], v[102:105], v[218:221], v[70:73]
	v_mfma_f32_16x16x32_bf16 v[78:81], v[86:89], v[218:221], 0
	v_mfma_f32_16x16x32_bf16 v[78:81], v[82:85], v[214:217], v[78:81]
	v_mfma_f32_16x16x32_bf16 v[138:141], v[150:153], v[190:193], 0
	v_mfma_f32_16x16x32_bf16 v[138:141], v[154:157], v[194:197], v[138:141]
	v_mfma_f32_16x16x32_bf16 v[130:133], v[186:189], v[194:197], 0
	v_mfma_f32_16x16x32_bf16 v[130:133], v[182:185], v[190:193], v[130:133]
	v_mfma_f32_16x16x32_bf16 v[114:117], v[182:185], v[198:201], 0
	v_mfma_f32_16x16x32_bf16 v[114:117], v[186:189], v[202:205], v[114:117]
	v_mfma_f32_16x16x32_bf16 v[122:125], v[154:157], v[202:205], 0
	v_mfma_f32_16x16x32_bf16 v[122:125], v[150:153], v[198:201], v[122:125]
	v_mfma_f32_16x16x32_bf16 v[106:109], v[150:153], v[206:209], 0
	v_mfma_f32_16x16x32_bf16 v[106:109], v[154:157], v[210:213], v[106:109]
	v_mfma_f32_16x16x32_bf16 v[90:93], v[186:189], v[210:213], 0
	v_mfma_f32_16x16x32_bf16 v[90:93], v[182:185], v[206:209], v[90:93]
	v_mfma_f32_16x16x32_bf16 v[66:69], v[182:185], v[214:217], 0
	v_mfma_f32_16x16x32_bf16 v[66:69], v[186:189], v[218:221], v[66:69]
	v_mfma_f32_16x16x32_bf16 v[74:77], v[154:157], v[218:221], 0
	v_mfma_f32_16x16x32_bf16 v[74:77], v[150:153], v[214:217], v[74:77]
	s_barrier
	s_setprio 0
	s_mov_b32 m0, s9
	s_mov_b32 s42, s78
	s_mov_b32 s43, s79
	ds_read_b128 v[190:193], v173 offset:16384
	ds_read_b128 v[194:197], v173 offset:17408
	ds_read_b128 v[198:201], v173 offset:18432
	ds_read_b128 v[202:205], v173 offset:19456
	ds_read_b128 v[206:209], v173 offset:20480
	ds_read_b128 v[210:213], v173 offset:21504
	ds_read_b128 v[214:217], v173 offset:22528
	ds_read_b128 v[218:221], v173 offset:23552
	buffer_load_dwordx4 v161, s[40:43], s54 offen lds
	s_mov_b32 m0, s10
	s_add_i32 s56, s54, 0x80000
	buffer_load_dwordx4 v165, s[40:43], s54 offen lds
	s_mov_b32 m0, s11
	s_nop 0
	buffer_load_dwordx4 v161, s[40:43], s56 offen lds
	s_mov_b32 m0, s12
	s_nop 0
	buffer_load_dwordx4 v165, s[40:43], s56 offen lds
	s_mov_b32 m0, s8
	s_nop 0
	buffer_load_dwordx4 v159, s[76:79], s55 offen lds
	s_mov_b32 m0, s13
	s_nop 0
	buffer_load_dwordx4 v163, s[76:79], s55 offen lds
	s_waitcnt vmcnt(8)
	s_waitcnt lgkmcnt(0)
	s_setprio 1
	s_barrier
	v_mfma_f32_16x16x32_bf16 v[62:65], v[82:85], v[190:193], 0
	v_mfma_f32_16x16x32_bf16 v[62:65], v[86:89], v[194:197], v[62:65]
	v_mfma_f32_16x16x32_bf16 v[54:57], v[102:105], v[194:197], 0
	v_mfma_f32_16x16x32_bf16 v[54:57], v[98:101], v[190:193], v[54:57]
	v_mfma_f32_16x16x32_bf16 v[38:41], v[98:101], v[198:201], 0
	v_mfma_f32_16x16x32_bf16 v[38:41], v[102:105], v[202:205], v[38:41]
	v_mfma_f32_16x16x32_bf16 v[46:49], v[86:89], v[202:205], 0
	v_mfma_f32_16x16x32_bf16 v[46:49], v[82:85], v[198:201], v[46:49]
	v_mfma_f32_16x16x32_bf16 v[30:33], v[82:85], v[206:209], 0
	v_mfma_f32_16x16x32_bf16 v[30:33], v[86:89], v[210:213], v[30:33]
	v_mfma_f32_16x16x32_bf16 v[22:25], v[102:105], v[210:213], 0
	v_mfma_f32_16x16x32_bf16 v[22:25], v[98:101], v[206:209], v[22:25]
	v_mfma_f32_16x16x32_bf16 v[6:9], v[98:101], v[214:217], 0
	v_mfma_f32_16x16x32_bf16 v[6:9], v[102:105], v[218:221], v[6:9]
	v_mfma_f32_16x16x32_bf16 v[14:17], v[86:89], v[218:221], 0
	v_mfma_f32_16x16x32_bf16 v[14:17], v[82:85], v[214:217], v[14:17]
	v_mfma_f32_16x16x32_bf16 v[58:61], v[150:153], v[190:193], 0
	v_mfma_f32_16x16x32_bf16 v[58:61], v[154:157], v[194:197], v[58:61]
	v_mfma_f32_16x16x32_bf16 v[50:53], v[186:189], v[194:197], 0
	v_mfma_f32_16x16x32_bf16 v[50:53], v[182:185], v[190:193], v[50:53]
	v_mfma_f32_16x16x32_bf16 v[34:37], v[182:185], v[198:201], 0
	v_mfma_f32_16x16x32_bf16 v[34:37], v[186:189], v[202:205], v[34:37]
	v_mfma_f32_16x16x32_bf16 v[42:45], v[154:157], v[202:205], 0
	v_mfma_f32_16x16x32_bf16 v[42:45], v[150:153], v[198:201], v[42:45]
	v_mfma_f32_16x16x32_bf16 v[26:29], v[150:153], v[206:209], 0
	v_mfma_f32_16x16x32_bf16 v[26:29], v[154:157], v[210:213], v[26:29]
	v_mfma_f32_16x16x32_bf16 v[18:21], v[186:189], v[210:213], 0
	v_mfma_f32_16x16x32_bf16 v[18:21], v[182:185], v[206:209], v[18:21]
	v_mfma_f32_16x16x32_bf16 v[2:5], v[182:185], v[214:217], 0
	v_mfma_f32_16x16x32_bf16 v[2:5], v[186:189], v[218:221], v[2:5]
	v_mfma_f32_16x16x32_bf16 v[10:13], v[154:157], v[218:221], 0
	v_mfma_f32_16x16x32_bf16 v[10:13], v[150:153], v[214:217], v[10:13]
	s_barrier
; #define PG8_STAGEX(rs, bufoff, soff, voff) do { _Pragma("unroll") for (int _i = 0; _i < 2; ++_i) \
;         __builtin_amdgcn_raw_ptr_buffer_load_lds(rs, (LAS unsigned*)(lds + (bufoff) + ldsw + _i * 8192), 16, (voff)[_i], (soff), 0, 0); } while (0)
; #define PG8_LDA(dst, b, h) do { _Pragma("unroll") for (int m = 0; m < 4; ++m) _Pragma("unroll") for (int k = 0; k < 2; ++k) dst[m][k] = *(const LAS bf16x8*)(lds + PG8_SA(b, h) + aoff + m * 2048 + k * 1024); } while (0)
; #define PG8_LDB(dst, b, h) do { _Pragma("unroll") for (int n = 0; n < 2; ++n) _Pragma("unroll") for (int k = 0; k < 2; ++k) dst[n][k] = *(const LAS bf16x8*)(lds + PG8_SB(b, h) + boff + n * 2048 + k * 1024); } while (0)
; #define PG8_WAIT_V(n) asm volatile("s_waitcnt vmcnt(" #n ")" ::: "memory")
; #define PG8_WAIT_L(n) asm volatile("s_waitcnt lgkmcnt(" #n ")" ::: "memory")
; #define PG8_BAR __builtin_amdgcn_s_barrier()
; #define PG8_SCHED __builtin_amdgcn_sched_barrier(0)
;     ...
;             PG8_LDB(B0, 1, 0); PG8_LDB(B1, 1, 1); PG8_SCHED; PG8_LDA(At, 1, 0); PG8_STAGEX(rsA, PG8_SA(0, 1), a2 + hstepA, voffA);
;             PG8_WAIT_V(8); PG8_WAIT_L(0); PG8_BAR; PG8_MMA(0, 0, At, B0); PG8_MMA(0, 1, At, B1); PG8_BAR; PG8_SCHED;
;             PG8_LDA(At, 1, 1); PG8_STAGEX(rsB, PG8_SB(1, 0), b3, voffB); PG8_STAGEX(rsB, PG8_SB(1, 1), b3 + hstepB, voffB); PG8_STAGEX(rsA, PG8_SA(1, 0), a3, voffA);
;             PG8_WAIT_V(8); PG8_WAIT_L(0); PG8_BAR; PG8_MMA(1, 0, At, B0); PG8_MMA(1, 1, At, B1); PG8_BAR; PG8_SCHED;
;         }
	s_setprio 0
	v_add_u32_e32 v102, 0x18000, v172
	v_add_u32_e32 v146, 0x1c000, v172
	ds_read_b128 v[82:85], v102
	ds_read_b128 v[86:89], v102 offset:1024
	ds_read_b128 v[98:101], v102 offset:2048
	ds_read_b128 v[102:105], v102 offset:3072
	ds_read_b128 v[150:153], v146
	ds_read_b128 v[154:157], v146 offset:1024
	ds_read_b128 v[182:185], v146 offset:2048
	ds_read_b128 v[186:189], v146 offset:3072
	s_add_i32 s55, s55, 0x80000
	s_mov_b32 m0, s14
	ds_read_b128 v[190:193], v173 offset:32768
	ds_read_b128 v[194:197], v173 offset:33792
	ds_read_b128 v[198:201], v173 offset:34816
	ds_read_b128 v[202:205], v173 offset:35840
	ds_read_b128 v[206:209], v173 offset:36864
	ds_read_b128 v[210:213], v173 offset:37888
	ds_read_b128 v[214:217], v173 offset:38912
	ds_read_b128 v[218:221], v173 offset:39936
	buffer_load_dwordx4 v159, s[76:79], s55 offen lds
	s_mov_b32 m0, s15
	s_nop 0
	buffer_load_dwordx4 v163, s[76:79], s55 offen lds
	s_waitcnt vmcnt(8)
	s_waitcnt lgkmcnt(0)
	s_setprio 1
	s_barrier
	v_mfma_f32_16x16x32_bf16 v[142:145], v[82:85], v[190:193], v[142:145]
	v_mfma_f32_16x16x32_bf16 v[142:145], v[86:89], v[194:197], v[142:145]
	v_mfma_f32_16x16x32_bf16 v[134:137], v[102:105], v[194:197], v[134:137]
	v_mfma_f32_16x16x32_bf16 v[134:137], v[98:101], v[190:193], v[134:137]
	v_mfma_f32_16x16x32_bf16 v[118:121], v[98:101], v[198:201], v[118:121]
	v_mfma_f32_16x16x32_bf16 v[118:121], v[102:105], v[202:205], v[118:121]
	v_mfma_f32_16x16x32_bf16 v[126:129], v[86:89], v[202:205], v[126:129]
	v_mfma_f32_16x16x32_bf16 v[126:129], v[82:85], v[198:201], v[126:129]
	v_mfma_f32_16x16x32_bf16 v[110:113], v[82:85], v[206:209], v[110:113]
	v_mfma_f32_16x16x32_bf16 v[110:113], v[86:89], v[210:213], v[110:113]
	v_mfma_f32_16x16x32_bf16 v[94:97], v[102:105], v[210:213], v[94:97]
	v_mfma_f32_16x16x32_bf16 v[94:97], v[98:101], v[206:209], v[94:97]
	v_mfma_f32_16x16x32_bf16 v[70:73], v[98:101], v[214:217], v[70:73]
	v_mfma_f32_16x16x32_bf16 v[70:73], v[102:105], v[218:221], v[70:73]
	v_mfma_f32_16x16x32_bf16 v[78:81], v[86:89], v[218:221], v[78:81]
	v_mfma_f32_16x16x32_bf16 v[78:81], v[82:85], v[214:217], v[78:81]
	v_mfma_f32_16x16x32_bf16 v[138:141], v[150:153], v[190:193], v[138:141]
	v_mfma_f32_16x16x32_bf16 v[138:141], v[154:157], v[194:197], v[138:141]
	v_mfma_f32_16x16x32_bf16 v[130:133], v[186:189], v[194:197], v[130:133]
	v_mfma_f32_16x16x32_bf16 v[130:133], v[182:185], v[190:193], v[130:133]
	v_mfma_f32_16x16x32_bf16 v[114:117], v[182:185], v[198:201], v[114:117]
	v_mfma_f32_16x16x32_bf16 v[114:117], v[186:189], v[202:205], v[114:117]
	v_mfma_f32_16x16x32_bf16 v[122:125], v[154:157], v[202:205], v[122:125]
	v_mfma_f32_16x16x32_bf16 v[122:125], v[150:153], v[198:201], v[122:125]
	v_mfma_f32_16x16x32_bf16 v[106:109], v[150:153], v[206:209], v[106:109]
	v_mfma_f32_16x16x32_bf16 v[106:109], v[154:157], v[210:213], v[106:109]
	v_mfma_f32_16x16x32_bf16 v[90:93], v[186:189], v[210:213], v[90:93]
	v_mfma_f32_16x16x32_bf16 v[90:93], v[182:185], v[206:209], v[90:93]
	v_mfma_f32_16x16x32_bf16 v[66:69], v[182:185], v[214:217], v[66:69]
	v_mfma_f32_16x16x32_bf16 v[66:69], v[186:189], v[218:221], v[66:69]
	v_mfma_f32_16x16x32_bf16 v[74:77], v[154:157], v[218:221], v[74:77]
	v_mfma_f32_16x16x32_bf16 v[74:77], v[150:153], v[214:217], v[74:77]
	s_barrier
	s_setprio 0
	s_mov_b32 m0, s16
	s_or_b32 s55, s54, 0x80
	ds_read_b128 v[190:193], v173 offset:49152
	ds_read_b128 v[194:197], v173 offset:50176
	ds_read_b128 v[198:201], v173 offset:51200
	ds_read_b128 v[202:205], v173 offset:52224
	ds_read_b128 v[206:209], v173 offset:53248
	ds_read_b128 v[210:213], v173 offset:54272
	ds_read_b128 v[214:217], v173 offset:55296
	ds_read_b128 v[218:221], v173 offset:56320
	buffer_load_dwordx4 v161, s[40:43], s55 offen lds
	s_mov_b32 m0, s17
	s_add_i32 s54, s54, 0x80080
	buffer_load_dwordx4 v165, s[40:43], s55 offen lds
	s_mov_b32 m0, s20
	s_nop 0
	buffer_load_dwordx4 v161, s[40:43], s54 offen lds
	s_mov_b32 m0, s21
	s_nop 0
	buffer_load_dwordx4 v165, s[40:43], s54 offen lds
	s_mov_b32 m0, s18
	s_nop 0
	buffer_load_dwordx4 v159, s[76:79], s53 offen lds
	s_mov_b32 m0, s19
	s_nop 0
	buffer_load_dwordx4 v163, s[76:79], s53 offen lds
	s_waitcnt vmcnt(8)
	s_waitcnt lgkmcnt(0)
	s_setprio 1
	s_barrier
	v_mfma_f32_16x16x32_bf16 v[62:65], v[82:85], v[190:193], v[62:65]
	v_mfma_f32_16x16x32_bf16 v[62:65], v[86:89], v[194:197], v[62:65]
	v_mfma_f32_16x16x32_bf16 v[54:57], v[102:105], v[194:197], v[54:57]
	v_mfma_f32_16x16x32_bf16 v[54:57], v[98:101], v[190:193], v[54:57]
	v_mfma_f32_16x16x32_bf16 v[38:41], v[98:101], v[198:201], v[38:41]
	v_mfma_f32_16x16x32_bf16 v[38:41], v[102:105], v[202:205], v[38:41]
	v_mfma_f32_16x16x32_bf16 v[46:49], v[86:89], v[202:205], v[46:49]
	v_mfma_f32_16x16x32_bf16 v[46:49], v[82:85], v[198:201], v[46:49]
	v_mfma_f32_16x16x32_bf16 v[30:33], v[82:85], v[206:209], v[30:33]
	v_mfma_f32_16x16x32_bf16 v[30:33], v[86:89], v[210:213], v[30:33]
	v_mfma_f32_16x16x32_bf16 v[22:25], v[102:105], v[210:213], v[22:25]
	v_mfma_f32_16x16x32_bf16 v[22:25], v[98:101], v[206:209], v[22:25]
	v_mfma_f32_16x16x32_bf16 v[6:9], v[98:101], v[214:217], v[6:9]
	v_mfma_f32_16x16x32_bf16 v[6:9], v[102:105], v[218:221], v[6:9]
	v_mfma_f32_16x16x32_bf16 v[14:17], v[86:89], v[218:221], v[14:17]
	v_mfma_f32_16x16x32_bf16 v[14:17], v[82:85], v[214:217], v[14:17]
	v_mfma_f32_16x16x32_bf16 v[58:61], v[150:153], v[190:193], v[58:61]
	v_mfma_f32_16x16x32_bf16 v[58:61], v[154:157], v[194:197], v[58:61]
	v_mfma_f32_16x16x32_bf16 v[50:53], v[186:189], v[194:197], v[50:53]
	v_mfma_f32_16x16x32_bf16 v[50:53], v[182:185], v[190:193], v[50:53]
	v_mfma_f32_16x16x32_bf16 v[34:37], v[182:185], v[198:201], v[34:37]
	v_mfma_f32_16x16x32_bf16 v[34:37], v[186:189], v[202:205], v[34:37]
	v_mfma_f32_16x16x32_bf16 v[42:45], v[154:157], v[202:205], v[42:45]
	v_mfma_f32_16x16x32_bf16 v[42:45], v[150:153], v[198:201], v[42:45]
	v_mfma_f32_16x16x32_bf16 v[26:29], v[150:153], v[206:209], v[26:29]
	v_mfma_f32_16x16x32_bf16 v[26:29], v[154:157], v[210:213], v[26:29]
	v_mfma_f32_16x16x32_bf16 v[18:21], v[186:189], v[210:213], v[18:21]
	v_mfma_f32_16x16x32_bf16 v[18:21], v[182:185], v[206:209], v[18:21]
	v_mfma_f32_16x16x32_bf16 v[2:5], v[182:185], v[214:217], v[2:5]
	v_mfma_f32_16x16x32_bf16 v[2:5], v[186:189], v[218:221], v[2:5]
	v_mfma_f32_16x16x32_bf16 v[10:13], v[154:157], v[218:221], v[10:13]
	v_mfma_f32_16x16x32_bf16 v[10:13], v[150:153], v[214:217], v[10:13]
	s_barrier
	s_setprio 0
	s_add_i32 s52, s52, 2
	s_addk_i32 s50, 0x100
	s_addk_i32 s51, 0x100
	.p2align	6

; #define PG8_STAGEX(rs, bufoff, soff, voff) do { _Pragma("unroll") for (int _i = 0; _i < 2; ++_i) \
;         __builtin_amdgcn_raw_ptr_buffer_load_lds(rs, (LAS unsigned*)(lds + (bufoff) + ldsw + _i * 8192), 16, (voff)[_i], (soff), 0, 0); } while (0)
; #define PG8_LDA(dst, b, h) do { _Pragma("unroll") for (int m = 0; m < 4; ++m) _Pragma("unroll") for (int k = 0; k < 2; ++k) dst[m][k] = *(const LAS bf16x8*)(lds + PG8_SA(b, h) + aoff + m * 2048 + k * 1024); } while (0)
; #define PG8_LDB(dst, b, h) do { _Pragma("unroll") for (int n = 0; n < 2; ++n) _Pragma("unroll") for (int k = 0; k < 2; ++k) dst[n][k] = *(const LAS bf16x8*)(lds + PG8_SB(b, h) + boff + n * 2048 + k * 1024); } while (0)
; #define PG8_WAIT_V(n) asm volatile("s_waitcnt vmcnt(" #n ")" ::: "memory")
; #define PG8_WAIT_L(n) asm volatile("s_waitcnt lgkmcnt(" #n ")" ::: "memory")
; #define PG8_BAR __builtin_amdgcn_s_barrier()
; #define PG8_SCHED __builtin_amdgcn_sched_barrier(0)
;     ...
;             PG8_LDB(B0, 0, 0); PG8_LDB(B1, 0, 1); PG8_SCHED; PG8_LDA(At, 0, 0); PG8_STAGEX(rsA, PG8_SA(1, 1), a1 + hstepA, voffA);
;             PG8_WAIT_V(8); PG8_WAIT_L(0); PG8_BAR; PG8_MMA(0, 0, At, B0); PG8_MMA(0, 1, At, B1); PG8_BAR; PG8_SCHED;
;             PG8_LDA(At, 0, 1); PG8_STAGEX(rsB, PG8_SB(0, 0), b2, voffB); PG8_STAGEX(rsB, PG8_SB(0, 1), b2 + hstepB, voffB); PG8_STAGEX(rsA, PG8_SA(0, 0), a2, voffA);
;             PG8_WAIT_V(8); PG8_WAIT_L(0); PG8_BAR; PG8_MMA(1, 0, At, B0); PG8_MMA(1, 1, At, B1); PG8_BAR; PG8_SCHED;
;     ...
;         if (!cur.keep) {
; #pragma unroll
;             for (int a = 0; a < 2; ++a)
; #pragma unroll
;                 for (int b = 0; b < 2; ++b)
; #pragma unroll
;                     for (int m = 0; m < 4; ++m)
; #pragma unroll
;                         for (int n = 0; n < 2; ++n) { f32x2 z0, z1; asm("v_mov_b64 %0, 0\n\tv_mov_b64 %1, 0" : "=v"(z0), "=v"(z1));
;                     acc[a][b][m][n] = __builtin_shufflevector(z0, z1, 0, 1, 2, 3); }
.LBB0_322:
	s_mul_i32 s74, s58, 0x2b0000
	s_and_b64 s[30:31], s[52:53], exec
	s_mul_i32 s75, s43, 0x2b0000
	s_waitcnt lgkmcnt(0)
	s_waitcnt vmcnt(15)
	s_mov_b32 s73, s58
	s_mov_b32 s72, s43
	s_cselect_b32 s30, s74, s51
	s_cselect_b32 s31, s75, s57
	s_add_i32 s51, s51, 0x158080
	s_addk_i32 s57, 0x100
	s_mov_b32 s58, -2
	v_add_u32_e32 v118, 0x10000, v210
	v_add_u32_e32 v160, 0x14000, v210
	ds_read_b128 v[106:109], v118
	ds_read_b128 v[110:113], v118 offset:1024
	ds_read_b128 v[114:117], v118 offset:2048
	ds_read_b128 v[118:121], v118 offset:3072
	ds_read_b128 v[122:125], v160
	ds_read_b128 v[134:137], v160 offset:1024
	ds_read_b128 v[156:159], v160 offset:2048
	ds_read_b128 v[160:163], v160 offset:3072
	s_add_i32 s42, s51, 0xffea8080
	s_cmpk_eq_i32 s58, 0x52
	s_cselect_b32 s61, s30, s42
	s_cselect_b32 s60, s31, s57
	s_or_b32 s59, s61, 0x80
	s_mov_b32 m0, s68
	ds_read_b128 v[164:167], v211
	ds_read_b128 v[168:171], v211 offset:1024
	ds_read_b128 v[182:185], v211 offset:2048
	ds_read_b128 v[186:189], v211 offset:3072
	ds_read_b128 v[190:193], v211 offset:4096
	ds_read_b128 v[194:197], v211 offset:5120
	ds_read_b128 v[198:201], v211 offset:6144
	ds_read_b128 v[202:205], v211 offset:7168
	buffer_load_dwordx4 v178, s[76:79], s51 offen lds
	s_mov_b32 m0, s69
	s_nop 0
	buffer_load_dwordx4 v206, s[76:79], s51 offen lds
	s_waitcnt vmcnt(8)
	s_waitcnt lgkmcnt(0)
	s_setprio 1
	s_barrier
	v_mfma_f32_16x16x32_bf16 v[150:153], v[106:109], v[164:167], 0
	v_mfma_f32_16x16x32_bf16 v[150:153], v[110:113], v[168:171], v[150:153]
	v_mfma_f32_16x16x32_bf16 v[146:149], v[118:121], v[168:171], 0
	v_mfma_f32_16x16x32_bf16 v[146:149], v[114:117], v[164:167], v[146:149]
	v_mfma_f32_16x16x32_bf16 v[138:141], v[114:117], v[182:185], 0
	v_mfma_f32_16x16x32_bf16 v[138:141], v[118:121], v[186:189], v[138:141]
	v_mfma_f32_16x16x32_bf16 v[142:145], v[110:113], v[186:189], 0
	v_mfma_f32_16x16x32_bf16 v[142:145], v[106:109], v[182:185], v[142:145]
	v_mfma_f32_16x16x32_bf16 v[130:133], v[106:109], v[190:193], 0
	v_mfma_f32_16x16x32_bf16 v[130:133], v[110:113], v[194:197], v[130:133]
	v_mfma_f32_16x16x32_bf16 v[126:129], v[118:121], v[194:197], 0
	v_mfma_f32_16x16x32_bf16 v[126:129], v[114:117], v[190:193], v[126:129]
	v_mfma_f32_16x16x32_bf16 v[98:101], v[114:117], v[198:201], 0
	v_mfma_f32_16x16x32_bf16 v[98:101], v[118:121], v[202:205], v[98:101]
	v_mfma_f32_16x16x32_bf16 v[102:105], v[110:113], v[202:205], 0
	v_mfma_f32_16x16x32_bf16 v[102:105], v[106:109], v[198:201], v[102:105]
	v_mfma_f32_16x16x32_bf16 v[62:65], v[122:125], v[164:167], 0
	v_mfma_f32_16x16x32_bf16 v[62:65], v[134:137], v[168:171], v[62:65]
	v_mfma_f32_16x16x32_bf16 v[58:61], v[160:163], v[168:171], 0
	v_mfma_f32_16x16x32_bf16 v[58:61], v[156:159], v[164:167], v[58:61]
	v_mfma_f32_16x16x32_bf16 v[50:53], v[156:159], v[182:185], 0
	v_mfma_f32_16x16x32_bf16 v[50:53], v[160:163], v[186:189], v[50:53]
	v_mfma_f32_16x16x32_bf16 v[54:57], v[134:137], v[186:189], 0
	v_mfma_f32_16x16x32_bf16 v[54:57], v[122:125], v[182:185], v[54:57]
	v_mfma_f32_16x16x32_bf16 v[46:49], v[122:125], v[190:193], 0
	v_mfma_f32_16x16x32_bf16 v[46:49], v[134:137], v[194:197], v[46:49]
	v_mfma_f32_16x16x32_bf16 v[42:45], v[160:163], v[194:197], 0
	v_mfma_f32_16x16x32_bf16 v[42:45], v[156:159], v[190:193], v[42:45]
	v_mfma_f32_16x16x32_bf16 v[34:37], v[156:159], v[198:201], 0
	v_mfma_f32_16x16x32_bf16 v[34:37], v[160:163], v[202:205], v[34:37]
	v_mfma_f32_16x16x32_bf16 v[38:41], v[134:137], v[202:205], 0
	v_mfma_f32_16x16x32_bf16 v[38:41], v[122:125], v[198:201], v[38:41]
	s_barrier
	s_setprio 0
	s_mov_b32 m0, s15
	s_mov_b32 s42, s78
	s_mov_b32 s43, s79
	ds_read_b128 v[164:167], v211 offset:16384
	ds_read_b128 v[168:171], v211 offset:17408
	ds_read_b128 v[182:185], v211 offset:18432
	ds_read_b128 v[186:189], v211 offset:19456
	ds_read_b128 v[190:193], v211 offset:20480
	ds_read_b128 v[194:197], v211 offset:21504
	ds_read_b128 v[198:201], v211 offset:22528
	ds_read_b128 v[202:205], v211 offset:23552
	buffer_load_dwordx4 v179, s[40:43], s60 offen lds
	s_mov_b32 m0, s16
	s_add_i32 s62, s60, 0x158000
	buffer_load_dwordx4 v207, s[40:43], s60 offen lds
	s_mov_b32 m0, s17
	s_nop 0
	buffer_load_dwordx4 v179, s[40:43], s62 offen lds
	s_mov_b32 m0, s18
	s_nop 0
	buffer_load_dwordx4 v207, s[40:43], s62 offen lds
	s_mov_b32 m0, s14
	s_nop 0
	buffer_load_dwordx4 v178, s[76:79], s61 offen lds
	s_mov_b32 m0, s19
	s_nop 0
	buffer_load_dwordx4 v206, s[76:79], s61 offen lds
	s_waitcnt vmcnt(8)
	s_waitcnt lgkmcnt(0)
	s_setprio 1
	s_barrier
	v_mfma_f32_16x16x32_bf16 v[94:97], v[106:109], v[164:167], 0
	v_mfma_f32_16x16x32_bf16 v[94:97], v[110:113], v[168:171], v[94:97]
	v_mfma_f32_16x16x32_bf16 v[90:93], v[118:121], v[168:171], 0
	v_mfma_f32_16x16x32_bf16 v[90:93], v[114:117], v[164:167], v[90:93]
	v_mfma_f32_16x16x32_bf16 v[82:85], v[114:117], v[182:185], 0
	v_mfma_f32_16x16x32_bf16 v[82:85], v[118:121], v[186:189], v[82:85]
	v_mfma_f32_16x16x32_bf16 v[86:89], v[110:113], v[186:189], 0
	v_mfma_f32_16x16x32_bf16 v[86:89], v[106:109], v[182:185], v[86:89]
	v_mfma_f32_16x16x32_bf16 v[78:81], v[106:109], v[190:193], 0
	v_mfma_f32_16x16x32_bf16 v[78:81], v[110:113], v[194:197], v[78:81]
	v_mfma_f32_16x16x32_bf16 v[74:77], v[118:121], v[194:197], 0
	v_mfma_f32_16x16x32_bf16 v[74:77], v[114:117], v[190:193], v[74:77]
	v_mfma_f32_16x16x32_bf16 v[66:69], v[114:117], v[198:201], 0
	v_mfma_f32_16x16x32_bf16 v[66:69], v[118:121], v[202:205], v[66:69]
	v_mfma_f32_16x16x32_bf16 v[70:73], v[110:113], v[202:205], 0
	v_mfma_f32_16x16x32_bf16 v[70:73], v[106:109], v[198:201], v[70:73]
	v_mfma_f32_16x16x32_bf16 v[30:33], v[122:125], v[164:167], 0
	v_mfma_f32_16x16x32_bf16 v[30:33], v[134:137], v[168:171], v[30:33]
	v_mfma_f32_16x16x32_bf16 v[26:29], v[160:163], v[168:171], 0
	v_mfma_f32_16x16x32_bf16 v[26:29], v[156:159], v[164:167], v[26:29]
	v_mfma_f32_16x16x32_bf16 v[18:21], v[156:159], v[182:185], 0
	v_mfma_f32_16x16x32_bf16 v[18:21], v[160:163], v[186:189], v[18:21]
	v_mfma_f32_16x16x32_bf16 v[22:25], v[134:137], v[186:189], 0
	v_mfma_f32_16x16x32_bf16 v[22:25], v[122:125], v[182:185], v[22:25]
	v_mfma_f32_16x16x32_bf16 v[14:17], v[122:125], v[190:193], 0
	v_mfma_f32_16x16x32_bf16 v[14:17], v[134:137], v[194:197], v[14:17]
	v_mfma_f32_16x16x32_bf16 v[10:13], v[160:163], v[194:197], 0
	v_mfma_f32_16x16x32_bf16 v[10:13], v[156:159], v[190:193], v[10:13]
	v_mfma_f32_16x16x32_bf16 v[2:5], v[156:159], v[198:201], 0
	v_mfma_f32_16x16x32_bf16 v[2:5], v[160:163], v[202:205], v[2:5]
	v_mfma_f32_16x16x32_bf16 v[6:9], v[134:137], v[202:205], 0
	v_mfma_f32_16x16x32_bf16 v[6:9], v[122:125], v[198:201], v[6:9]
	s_barrier
; #define PG8_STAGEX(rs, bufoff, soff, voff) do { _Pragma("unroll") for (int _i = 0; _i < 2; ++_i) \
;         __builtin_amdgcn_raw_ptr_buffer_load_lds(rs, (LAS unsigned*)(lds + (bufoff) + ldsw + _i * 8192), 16, (voff)[_i], (soff), 0, 0); } while (0)
; #define PG8_LDA(dst, b, h) do { _Pragma("unroll") for (int m = 0; m < 4; ++m) _Pragma("unroll") for (int k = 0; k < 2; ++k) dst[m][k] = *(const LAS bf16x8*)(lds + PG8_SA(b, h) + aoff + m * 2048 + k * 1024); } while (0)
; #define PG8_LDB(dst, b, h) do { _Pragma("unroll") for (int n = 0; n < 2; ++n) _Pragma("unroll") for (int k = 0; k < 2; ++k) dst[n][k] = *(const LAS bf16x8*)(lds + PG8_SB(b, h) + boff + n * 2048 + k * 1024); } while (0)
; #define PG8_WAIT_V(n) asm volatile("s_waitcnt vmcnt(" #n ")" ::: "memory")
; #define PG8_WAIT_L(n) asm volatile("s_waitcnt lgkmcnt(" #n ")" ::: "memory")
; #define PG8_BAR __builtin_amdgcn_s_barrier()
; #define PG8_SCHED __builtin_amdgcn_sched_barrier(0)
;     ...
;             PG8_LDB(B0, 1, 0); PG8_LDB(B1, 1, 1); PG8_SCHED; PG8_LDA(At, 1, 0); PG8_STAGEX(rsA, PG8_SA(0, 1), a2 + hstepA, voffA);
;             PG8_WAIT_V(8); PG8_WAIT_L(0); PG8_BAR; PG8_MMA(0, 0, At, B0); PG8_MMA(0, 1, At, B1); PG8_BAR; PG8_SCHED;
;             PG8_LDA(At, 1, 1); PG8_STAGEX(rsB, PG8_SB(1, 0), b3, voffB); PG8_STAGEX(rsB, PG8_SB(1, 1), b3 + hstepB, voffB); PG8_STAGEX(rsA, PG8_SA(1, 0), a3, voffA);
;             PG8_WAIT_V(8); PG8_WAIT_L(0); PG8_BAR; PG8_MMA(1, 0, At, B0); PG8_MMA(1, 1, At, B1); PG8_BAR; PG8_SCHED;
;         }
	s_setprio 0
	v_add_u32_e32 v118, 0x18000, v210
	v_add_u32_e32 v160, 0x1c000, v210
	ds_read_b128 v[106:109], v118
	ds_read_b128 v[110:113], v118 offset:1024
	ds_read_b128 v[114:117], v118 offset:2048
	ds_read_b128 v[118:121], v118 offset:3072
	ds_read_b128 v[122:125], v160
	ds_read_b128 v[134:137], v160 offset:1024
	ds_read_b128 v[156:159], v160 offset:2048
	ds_read_b128 v[160:163], v160 offset:3072
	s_add_i32 s61, s61, 0x158000
	s_mov_b32 m0, s20
	ds_read_b128 v[164:167], v211 offset:32768
	ds_read_b128 v[168:171], v211 offset:33792
	ds_read_b128 v[182:185], v211 offset:34816
	ds_read_b128 v[186:189], v211 offset:35840
	ds_read_b128 v[190:193], v211 offset:36864
	ds_read_b128 v[194:197], v211 offset:37888
	ds_read_b128 v[198:201], v211 offset:38912
	ds_read_b128 v[202:205], v211 offset:39936
	buffer_load_dwordx4 v178, s[76:79], s61 offen lds
	s_mov_b32 m0, s21
	s_nop 0
	buffer_load_dwordx4 v206, s[76:79], s61 offen lds
	s_waitcnt vmcnt(8)
	s_waitcnt lgkmcnt(0)
	s_setprio 1
	s_barrier
	v_mfma_f32_16x16x32_bf16 v[150:153], v[106:109], v[164:167], v[150:153]
	v_mfma_f32_16x16x32_bf16 v[150:153], v[110:113], v[168:171], v[150:153]
	v_mfma_f32_16x16x32_bf16 v[146:149], v[118:121], v[168:171], v[146:149]
	v_mfma_f32_16x16x32_bf16 v[146:149], v[114:117], v[164:167], v[146:149]
	v_mfma_f32_16x16x32_bf16 v[138:141], v[114:117], v[182:185], v[138:141]
	v_mfma_f32_16x16x32_bf16 v[138:141], v[118:121], v[186:189], v[138:141]
	v_mfma_f32_16x16x32_bf16 v[142:145], v[110:113], v[186:189], v[142:145]
	v_mfma_f32_16x16x32_bf16 v[142:145], v[106:109], v[182:185], v[142:145]
	v_mfma_f32_16x16x32_bf16 v[130:133], v[106:109], v[190:193], v[130:133]
	v_mfma_f32_16x16x32_bf16 v[130:133], v[110:113], v[194:197], v[130:133]
	v_mfma_f32_16x16x32_bf16 v[126:129], v[118:121], v[194:197], v[126:129]
	v_mfma_f32_16x16x32_bf16 v[126:129], v[114:117], v[190:193], v[126:129]
	v_mfma_f32_16x16x32_bf16 v[98:101], v[114:117], v[198:201], v[98:101]
	v_mfma_f32_16x16x32_bf16 v[98:101], v[118:121], v[202:205], v[98:101]
	v_mfma_f32_16x16x32_bf16 v[102:105], v[110:113], v[202:205], v[102:105]
	v_mfma_f32_16x16x32_bf16 v[102:105], v[106:109], v[198:201], v[102:105]
	v_mfma_f32_16x16x32_bf16 v[62:65], v[122:125], v[164:167], v[62:65]
	v_mfma_f32_16x16x32_bf16 v[62:65], v[134:137], v[168:171], v[62:65]
	v_mfma_f32_16x16x32_bf16 v[58:61], v[160:163], v[168:171], v[58:61]
	v_mfma_f32_16x16x32_bf16 v[58:61], v[156:159], v[164:167], v[58:61]
	v_mfma_f32_16x16x32_bf16 v[50:53], v[156:159], v[182:185], v[50:53]
	v_mfma_f32_16x16x32_bf16 v[50:53], v[160:163], v[186:189], v[50:53]
	v_mfma_f32_16x16x32_bf16 v[54:57], v[134:137], v[186:189], v[54:57]
	v_mfma_f32_16x16x32_bf16 v[54:57], v[122:125], v[182:185], v[54:57]
	v_mfma_f32_16x16x32_bf16 v[46:49], v[122:125], v[190:193], v[46:49]
	v_mfma_f32_16x16x32_bf16 v[46:49], v[134:137], v[194:197], v[46:49]
	v_mfma_f32_16x16x32_bf16 v[42:45], v[160:163], v[194:197], v[42:45]
	v_mfma_f32_16x16x32_bf16 v[42:45], v[156:159], v[190:193], v[42:45]
	v_mfma_f32_16x16x32_bf16 v[34:37], v[156:159], v[198:201], v[34:37]
	v_mfma_f32_16x16x32_bf16 v[34:37], v[160:163], v[202:205], v[34:37]
	v_mfma_f32_16x16x32_bf16 v[38:41], v[134:137], v[202:205], v[38:41]
	v_mfma_f32_16x16x32_bf16 v[38:41], v[122:125], v[198:201], v[38:41]
	s_barrier
	s_setprio 0
	s_mov_b32 m0, s28
	s_or_b32 s61, s60, 0x80
	ds_read_b128 v[164:167], v211 offset:49152
	ds_read_b128 v[168:171], v211 offset:50176
	ds_read_b128 v[182:185], v211 offset:51200
	ds_read_b128 v[186:189], v211 offset:52224
	ds_read_b128 v[190:193], v211 offset:53248
	ds_read_b128 v[194:197], v211 offset:54272
	ds_read_b128 v[198:201], v211 offset:55296
	ds_read_b128 v[202:205], v211 offset:56320
	buffer_load_dwordx4 v179, s[40:43], s61 offen lds
	s_mov_b32 m0, s29
	s_add_i32 s60, s60, 0x158080
	buffer_load_dwordx4 v207, s[40:43], s61 offen lds
	s_mov_b32 m0, s66
	s_nop 0
	buffer_load_dwordx4 v179, s[40:43], s60 offen lds
	s_mov_b32 m0, s67
	s_nop 0
	buffer_load_dwordx4 v207, s[40:43], s60 offen lds
	s_mov_b32 m0, s54
	s_nop 0
	buffer_load_dwordx4 v178, s[76:79], s59 offen lds
	s_mov_b32 m0, s55
	s_nop 0
	buffer_load_dwordx4 v206, s[76:79], s59 offen lds
	s_waitcnt vmcnt(8)
	s_waitcnt lgkmcnt(0)
	s_setprio 1
	s_barrier
	v_mfma_f32_16x16x32_bf16 v[94:97], v[106:109], v[164:167], v[94:97]
	v_mfma_f32_16x16x32_bf16 v[94:97], v[110:113], v[168:171], v[94:97]
	v_mfma_f32_16x16x32_bf16 v[90:93], v[118:121], v[168:171], v[90:93]
	v_mfma_f32_16x16x32_bf16 v[90:93], v[114:117], v[164:167], v[90:93]
	v_mfma_f32_16x16x32_bf16 v[82:85], v[114:117], v[182:185], v[82:85]
	v_mfma_f32_16x16x32_bf16 v[82:85], v[118:121], v[186:189], v[82:85]
	v_mfma_f32_16x16x32_bf16 v[86:89], v[110:113], v[186:189], v[86:89]
	v_mfma_f32_16x16x32_bf16 v[86:89], v[106:109], v[182:185], v[86:89]
	v_mfma_f32_16x16x32_bf16 v[78:81], v[106:109], v[190:193], v[78:81]
	v_mfma_f32_16x16x32_bf16 v[78:81], v[110:113], v[194:197], v[78:81]
	v_mfma_f32_16x16x32_bf16 v[74:77], v[118:121], v[194:197], v[74:77]
	v_mfma_f32_16x16x32_bf16 v[74:77], v[114:117], v[190:193], v[74:77]
	v_mfma_f32_16x16x32_bf16 v[66:69], v[114:117], v[198:201], v[66:69]
	v_mfma_f32_16x16x32_bf16 v[66:69], v[118:121], v[202:205], v[66:69]
	v_mfma_f32_16x16x32_bf16 v[70:73], v[110:113], v[202:205], v[70:73]
	v_mfma_f32_16x16x32_bf16 v[70:73], v[106:109], v[198:201], v[70:73]
	v_mfma_f32_16x16x32_bf16 v[30:33], v[122:125], v[164:167], v[30:33]
	v_mfma_f32_16x16x32_bf16 v[30:33], v[134:137], v[168:171], v[30:33]
	v_mfma_f32_16x16x32_bf16 v[26:29], v[160:163], v[168:171], v[26:29]
	v_mfma_f32_16x16x32_bf16 v[26:29], v[156:159], v[164:167], v[26:29]
	v_mfma_f32_16x16x32_bf16 v[18:21], v[156:159], v[182:185], v[18:21]
	v_mfma_f32_16x16x32_bf16 v[18:21], v[160:163], v[186:189], v[18:21]
	v_mfma_f32_16x16x32_bf16 v[22:25], v[134:137], v[186:189], v[22:25]
	v_mfma_f32_16x16x32_bf16 v[22:25], v[122:125], v[182:185], v[22:25]
	v_mfma_f32_16x16x32_bf16 v[14:17], v[122:125], v[190:193], v[14:17]
	v_mfma_f32_16x16x32_bf16 v[14:17], v[134:137], v[194:197], v[14:17]
	v_mfma_f32_16x16x32_bf16 v[10:13], v[160:163], v[194:197], v[10:13]
	v_mfma_f32_16x16x32_bf16 v[10:13], v[156:159], v[190:193], v[10:13]
	v_mfma_f32_16x16x32_bf16 v[2:5], v[156:159], v[198:201], v[2:5]
	v_mfma_f32_16x16x32_bf16 v[2:5], v[160:163], v[202:205], v[2:5]
	v_mfma_f32_16x16x32_bf16 v[6:9], v[134:137], v[202:205], v[6:9]
	v_mfma_f32_16x16x32_bf16 v[6:9], v[122:125], v[198:201], v[6:9]
	s_barrier
	s_setprio 0
	s_add_i32 s58, s58, 2
	s_addk_i32 s51, 0x100
	s_addk_i32 s57, 0x100
	.p2align	6

; #define PG8_STAGEX(rs, bufoff, soff, voff) do { _Pragma("unroll") for (int _i = 0; _i < 2; ++_i) \
;         __builtin_amdgcn_raw_ptr_buffer_load_lds(rs, (LAS unsigned*)(lds + (bufoff) + ldsw + _i * 8192), 16, (voff)[_i], (soff), 0, 0); } while (0)
; #define PG8_LDA(dst, b, h) do { _Pragma("unroll") for (int m = 0; m < 4; ++m) _Pragma("unroll") for (int k = 0; k < 2; ++k) dst[m][k] = *(const LAS bf16x8*)(lds + PG8_SA(b, h) + aoff + m * 2048 + k * 1024); } while (0)
; #define PG8_LDB(dst, b, h) do { _Pragma("unroll") for (int n = 0; n < 2; ++n) _Pragma("unroll") for (int k = 0; k < 2; ++k) dst[n][k] = *(const LAS bf16x8*)(lds + PG8_SB(b, h) + boff + n * 2048 + k * 1024); } while (0)
; #define PG8_WAIT_V(n) asm volatile("s_waitcnt vmcnt(" #n ")" ::: "memory")
; #define PG8_WAIT_L(n) asm volatile("s_waitcnt lgkmcnt(" #n ")" ::: "memory")
; #define PG8_BAR __builtin_amdgcn_s_barrier()
; #define PG8_SCHED __builtin_amdgcn_sched_barrier(0)
;     ...
;             PG8_LDB(B0, 0, 0); PG8_LDB(B1, 0, 1); PG8_SCHED; PG8_LDA(At, 0, 0); PG8_STAGEX(rsA, PG8_SA(1, 1), a1 + hstepA, voffA);
;             PG8_WAIT_V(8); PG8_WAIT_L(0); PG8_BAR; PG8_MMA(0, 0, At, B0); PG8_MMA(0, 1, At, B1); PG8_BAR; PG8_SCHED;
;             PG8_LDA(At, 0, 1); PG8_STAGEX(rsB, PG8_SB(0, 0), b2, voffB); PG8_STAGEX(rsB, PG8_SB(0, 1), b2 + hstepB, voffB); PG8_STAGEX(rsA, PG8_SA(0, 0), a2, voffA);
;             PG8_WAIT_V(8); PG8_WAIT_L(0); PG8_BAR; PG8_MMA(1, 0, At, B0); PG8_MMA(1, 1, At, B1); PG8_BAR; PG8_SCHED;
;     ...
;         if (!cur.keep) {
; #pragma unroll
;             for (int a = 0; a < 2; ++a)
; #pragma unroll
;                 for (int b = 0; b < 2; ++b)
; #pragma unroll
;                     for (int m = 0; m < 4; ++m)
; #pragma unroll
;                         for (int n = 0; n < 2; ++n) { f32x2 z0, z1; asm("v_mov_b64 %0, 0\n\tv_mov_b64 %1, 0" : "=v"(z0), "=v"(z1));
;                     acc[a][b][m][n] = __builtin_shufflevector(z0, z1, 0, 1, 2, 3); }
.LBB0_1273:
	s_lshl_b32 s65, s64, 20
	s_and_b64 s[30:31], s[38:39], exec
	s_cselect_b32 s30, s65, s62
	s_lshl_b32 s66, s59, 20
	s_and_b64 s[42:43], s[38:39], exec
	s_waitcnt vmcnt(15)
	s_cselect_b32 s31, s66, s63
	s_add_i32 s62, s62, 0x80080
	s_addk_i32 s63, 0x100
	s_mov_b32 s67, -2
	v_add_u32_e32 v142, 0x10000, v157
	v_add_u32_e32 v159, 0x14000, v157
	ds_read_b128 v[130:133], v142
	ds_read_b128 v[134:137], v142 offset:1024
	ds_read_b128 v[138:141], v142 offset:2048
	ds_read_b128 v[142:145], v142 offset:3072
	ds_read_b128 v[146:149], v159
	ds_read_b128 v[164:167], v159 offset:1024
	ds_read_b128 v[168:171], v159 offset:2048
	ds_read_b128 v[182:185], v159 offset:3072
	s_add_i32 s42, s62, 0xfff80080
	s_cmp_eq_u32 s67, 28
	s_cselect_b32 s70, s30, s42
	s_cselect_b32 s69, s31, s63
	s_or_b32 s68, s70, 0x80
	s_mov_b32 m0, s29
	ds_read_b128 v[186:189], v158
	ds_read_b128 v[190:193], v158 offset:1024
	ds_read_b128 v[194:197], v158 offset:2048
	ds_read_b128 v[198:201], v158 offset:3072
	ds_read_b128 v[202:205], v158 offset:4096
	ds_read_b128 v[206:209], v158 offset:5120
	ds_read_b128 v[210:213], v158 offset:6144
	ds_read_b128 v[214:217], v158 offset:7168
	buffer_load_dwordx4 v150, s[76:79], s62 offen lds
	s_mov_b32 m0, s35
	s_nop 0
	buffer_load_dwordx4 v152, s[76:79], s62 offen lds
	s_waitcnt vmcnt(8)
	s_waitcnt lgkmcnt(0)
	s_setprio 1
	s_barrier
	v_mfma_f32_16x16x32_bf16 v[126:129], v[130:133], v[186:189], 0
	v_mfma_f32_16x16x32_bf16 v[126:129], v[134:137], v[190:193], v[126:129]
	v_mfma_f32_16x16x32_bf16 v[122:125], v[142:145], v[190:193], 0
	v_mfma_f32_16x16x32_bf16 v[122:125], v[138:141], v[186:189], v[122:125]
	v_mfma_f32_16x16x32_bf16 v[114:117], v[138:141], v[194:197], 0
	v_mfma_f32_16x16x32_bf16 v[114:117], v[142:145], v[198:201], v[114:117]
	v_mfma_f32_16x16x32_bf16 v[118:121], v[134:137], v[198:201], 0
	v_mfma_f32_16x16x32_bf16 v[118:121], v[130:133], v[194:197], v[118:121]
	v_mfma_f32_16x16x32_bf16 v[110:113], v[130:133], v[202:205], 0
	v_mfma_f32_16x16x32_bf16 v[110:113], v[134:137], v[206:209], v[110:113]
	v_mfma_f32_16x16x32_bf16 v[106:109], v[142:145], v[206:209], 0
	v_mfma_f32_16x16x32_bf16 v[106:109], v[138:141], v[202:205], v[106:109]
	v_mfma_f32_16x16x32_bf16 v[98:101], v[138:141], v[210:213], 0
	v_mfma_f32_16x16x32_bf16 v[98:101], v[142:145], v[214:217], v[98:101]
	v_mfma_f32_16x16x32_bf16 v[102:105], v[134:137], v[214:217], 0
	v_mfma_f32_16x16x32_bf16 v[102:105], v[130:133], v[210:213], v[102:105]
	v_mfma_f32_16x16x32_bf16 v[62:65], v[146:149], v[186:189], 0
	v_mfma_f32_16x16x32_bf16 v[62:65], v[164:167], v[190:193], v[62:65]
	v_mfma_f32_16x16x32_bf16 v[58:61], v[182:185], v[190:193], 0
	v_mfma_f32_16x16x32_bf16 v[58:61], v[168:171], v[186:189], v[58:61]
	v_mfma_f32_16x16x32_bf16 v[50:53], v[168:171], v[194:197], 0
	v_mfma_f32_16x16x32_bf16 v[50:53], v[182:185], v[198:201], v[50:53]
	v_mfma_f32_16x16x32_bf16 v[54:57], v[164:167], v[198:201], 0
	v_mfma_f32_16x16x32_bf16 v[54:57], v[146:149], v[194:197], v[54:57]
	v_mfma_f32_16x16x32_bf16 v[46:49], v[146:149], v[202:205], 0
	v_mfma_f32_16x16x32_bf16 v[46:49], v[164:167], v[206:209], v[46:49]
	v_mfma_f32_16x16x32_bf16 v[42:45], v[182:185], v[206:209], 0
	v_mfma_f32_16x16x32_bf16 v[42:45], v[168:171], v[202:205], v[42:45]
	v_mfma_f32_16x16x32_bf16 v[34:37], v[168:171], v[210:213], 0
	v_mfma_f32_16x16x32_bf16 v[34:37], v[182:185], v[214:217], v[34:37]
	v_mfma_f32_16x16x32_bf16 v[38:41], v[164:167], v[214:217], 0
	v_mfma_f32_16x16x32_bf16 v[38:41], v[146:149], v[210:213], v[38:41]
	s_barrier
	s_setprio 0
	s_mov_b32 m0, s16
	s_mov_b32 s42, s78
	s_mov_b32 s43, s79
	ds_read_b128 v[186:189], v158 offset:16384
	ds_read_b128 v[190:193], v158 offset:17408
	ds_read_b128 v[194:197], v158 offset:18432
	ds_read_b128 v[198:201], v158 offset:19456
	ds_read_b128 v[202:205], v158 offset:20480
	ds_read_b128 v[206:209], v158 offset:21504
	ds_read_b128 v[210:213], v158 offset:22528
	ds_read_b128 v[214:217], v158 offset:23552
	buffer_load_dwordx4 v151, s[40:43], s69 offen lds
	s_mov_b32 m0, s17
	s_add_i32 s71, s69, 0x80000
	buffer_load_dwordx4 v153, s[40:43], s69 offen lds
	s_mov_b32 m0, s18
	s_nop 0
	buffer_load_dwordx4 v151, s[40:43], s71 offen lds
	s_mov_b32 m0, s19
	s_nop 0
	buffer_load_dwordx4 v153, s[40:43], s71 offen lds
	s_mov_b32 m0, s15
	s_nop 0
	buffer_load_dwordx4 v150, s[76:79], s70 offen lds
	s_mov_b32 m0, s20
	s_nop 0
	buffer_load_dwordx4 v152, s[76:79], s70 offen lds
	s_waitcnt vmcnt(8)
	s_waitcnt lgkmcnt(0)
	s_setprio 1
	s_barrier
	v_mfma_f32_16x16x32_bf16 v[94:97], v[130:133], v[186:189], 0
	v_mfma_f32_16x16x32_bf16 v[94:97], v[134:137], v[190:193], v[94:97]
	v_mfma_f32_16x16x32_bf16 v[90:93], v[142:145], v[190:193], 0
	v_mfma_f32_16x16x32_bf16 v[90:93], v[138:141], v[186:189], v[90:93]
	v_mfma_f32_16x16x32_bf16 v[82:85], v[138:141], v[194:197], 0
	v_mfma_f32_16x16x32_bf16 v[82:85], v[142:145], v[198:201], v[82:85]
	v_mfma_f32_16x16x32_bf16 v[86:89], v[134:137], v[198:201], 0
	v_mfma_f32_16x16x32_bf16 v[86:89], v[130:133], v[194:197], v[86:89]
	v_mfma_f32_16x16x32_bf16 v[78:81], v[130:133], v[202:205], 0
	v_mfma_f32_16x16x32_bf16 v[78:81], v[134:137], v[206:209], v[78:81]
	v_mfma_f32_16x16x32_bf16 v[74:77], v[142:145], v[206:209], 0
	v_mfma_f32_16x16x32_bf16 v[74:77], v[138:141], v[202:205], v[74:77]
	v_mfma_f32_16x16x32_bf16 v[66:69], v[138:141], v[210:213], 0
	v_mfma_f32_16x16x32_bf16 v[66:69], v[142:145], v[214:217], v[66:69]
	v_mfma_f32_16x16x32_bf16 v[70:73], v[134:137], v[214:217], 0
	v_mfma_f32_16x16x32_bf16 v[70:73], v[130:133], v[210:213], v[70:73]
	v_mfma_f32_16x16x32_bf16 v[30:33], v[146:149], v[186:189], 0
	v_mfma_f32_16x16x32_bf16 v[30:33], v[164:167], v[190:193], v[30:33]
	v_mfma_f32_16x16x32_bf16 v[26:29], v[182:185], v[190:193], 0
	v_mfma_f32_16x16x32_bf16 v[26:29], v[168:171], v[186:189], v[26:29]
	v_mfma_f32_16x16x32_bf16 v[18:21], v[168:171], v[194:197], 0
	v_mfma_f32_16x16x32_bf16 v[18:21], v[182:185], v[198:201], v[18:21]
	v_mfma_f32_16x16x32_bf16 v[22:25], v[164:167], v[198:201], 0
	v_mfma_f32_16x16x32_bf16 v[22:25], v[146:149], v[194:197], v[22:25]
	v_mfma_f32_16x16x32_bf16 v[14:17], v[146:149], v[202:205], 0
	v_mfma_f32_16x16x32_bf16 v[14:17], v[164:167], v[206:209], v[14:17]
	v_mfma_f32_16x16x32_bf16 v[10:13], v[182:185], v[206:209], 0
	v_mfma_f32_16x16x32_bf16 v[10:13], v[168:171], v[202:205], v[10:13]
	v_mfma_f32_16x16x32_bf16 v[2:5], v[168:171], v[210:213], 0
	v_mfma_f32_16x16x32_bf16 v[2:5], v[182:185], v[214:217], v[2:5]
	v_mfma_f32_16x16x32_bf16 v[6:9], v[164:167], v[214:217], 0
	v_mfma_f32_16x16x32_bf16 v[6:9], v[146:149], v[210:213], v[6:9]
	s_barrier
; #define PG8_STAGEX(rs, bufoff, soff, voff) do { _Pragma("unroll") for (int _i = 0; _i < 2; ++_i) \
;         __builtin_amdgcn_raw_ptr_buffer_load_lds(rs, (LAS unsigned*)(lds + (bufoff) + ldsw + _i * 8192), 16, (voff)[_i], (soff), 0, 0); } while (0)
; #define PG8_LDA(dst, b, h) do { _Pragma("unroll") for (int m = 0; m < 4; ++m) _Pragma("unroll") for (int k = 0; k < 2; ++k) dst[m][k] = *(const LAS bf16x8*)(lds + PG8_SA(b, h) + aoff + m * 2048 + k * 1024); } while (0)
; #define PG8_LDB(dst, b, h) do { _Pragma("unroll") for (int n = 0; n < 2; ++n) _Pragma("unroll") for (int k = 0; k < 2; ++k) dst[n][k] = *(const LAS bf16x8*)(lds + PG8_SB(b, h) + boff + n * 2048 + k * 1024); } while (0)
; #define PG8_WAIT_V(n) asm volatile("s_waitcnt vmcnt(" #n ")" ::: "memory")
; #define PG8_WAIT_L(n) asm volatile("s_waitcnt lgkmcnt(" #n ")" ::: "memory")
; #define PG8_BAR __builtin_amdgcn_s_barrier()
; #define PG8_SCHED __builtin_amdgcn_sched_barrier(0)
;     ...
;             PG8_LDB(B0, 1, 0); PG8_LDB(B1, 1, 1); PG8_SCHED; PG8_LDA(At, 1, 0); PG8_STAGEX(rsA, PG8_SA(0, 1), a2 + hstepA, voffA);
;             PG8_WAIT_V(8); PG8_WAIT_L(0); PG8_BAR; PG8_MMA(0, 0, At, B0); PG8_MMA(0, 1, At, B1); PG8_BAR; PG8_SCHED;
;             PG8_LDA(At, 1, 1); PG8_STAGEX(rsB, PG8_SB(1, 0), b3, voffB); PG8_STAGEX(rsB, PG8_SB(1, 1), b3 + hstepB, voffB); PG8_STAGEX(rsA, PG8_SA(1, 0), a3, voffA);
;             PG8_WAIT_V(8); PG8_WAIT_L(0); PG8_BAR; PG8_MMA(1, 0, At, B0); PG8_MMA(1, 1, At, B1); PG8_BAR; PG8_SCHED;
	s_setprio 0
	v_add_u32_e32 v142, 0x18000, v157
	v_add_u32_e32 v159, 0x1c000, v157
	ds_read_b128 v[130:133], v142
	ds_read_b128 v[134:137], v142 offset:1024
	ds_read_b128 v[138:141], v142 offset:2048
	ds_read_b128 v[142:145], v142 offset:3072
	ds_read_b128 v[146:149], v159
	ds_read_b128 v[164:167], v159 offset:1024
	ds_read_b128 v[168:171], v159 offset:2048
	ds_read_b128 v[182:185], v159 offset:3072
	s_add_i32 s70, s70, 0x80000
	s_mov_b32 m0, s21
	ds_read_b128 v[186:189], v158 offset:32768
	ds_read_b128 v[190:193], v158 offset:33792
	ds_read_b128 v[194:197], v158 offset:34816
	ds_read_b128 v[198:201], v158 offset:35840
	ds_read_b128 v[202:205], v158 offset:36864
	ds_read_b128 v[206:209], v158 offset:37888
	ds_read_b128 v[210:213], v158 offset:38912
	ds_read_b128 v[214:217], v158 offset:39936
	buffer_load_dwordx4 v150, s[76:79], s70 offen lds
	s_mov_b32 m0, s22
	s_nop 0
	buffer_load_dwordx4 v152, s[76:79], s70 offen lds
	s_waitcnt vmcnt(8)
	s_waitcnt lgkmcnt(0)
	s_setprio 1
	s_barrier
	v_mfma_f32_16x16x32_bf16 v[126:129], v[130:133], v[186:189], v[126:129]
	v_mfma_f32_16x16x32_bf16 v[126:129], v[134:137], v[190:193], v[126:129]
	v_mfma_f32_16x16x32_bf16 v[122:125], v[142:145], v[190:193], v[122:125]
	v_mfma_f32_16x16x32_bf16 v[122:125], v[138:141], v[186:189], v[122:125]
	v_mfma_f32_16x16x32_bf16 v[114:117], v[138:141], v[194:197], v[114:117]
	v_mfma_f32_16x16x32_bf16 v[114:117], v[142:145], v[198:201], v[114:117]
	v_mfma_f32_16x16x32_bf16 v[118:121], v[134:137], v[198:201], v[118:121]
	v_mfma_f32_16x16x32_bf16 v[118:121], v[130:133], v[194:197], v[118:121]
	v_mfma_f32_16x16x32_bf16 v[110:113], v[130:133], v[202:205], v[110:113]
	v_mfma_f32_16x16x32_bf16 v[110:113], v[134:137], v[206:209], v[110:113]
	v_mfma_f32_16x16x32_bf16 v[106:109], v[142:145], v[206:209], v[106:109]
	v_mfma_f32_16x16x32_bf16 v[106:109], v[138:141], v[202:205], v[106:109]
	v_mfma_f32_16x16x32_bf16 v[98:101], v[138:141], v[210:213], v[98:101]
	v_mfma_f32_16x16x32_bf16 v[98:101], v[142:145], v[214:217], v[98:101]
	v_mfma_f32_16x16x32_bf16 v[102:105], v[134:137], v[214:217], v[102:105]
	v_mfma_f32_16x16x32_bf16 v[102:105], v[130:133], v[210:213], v[102:105]
	v_mfma_f32_16x16x32_bf16 v[62:65], v[146:149], v[186:189], v[62:65]
	v_mfma_f32_16x16x32_bf16 v[62:65], v[164:167], v[190:193], v[62:65]
	v_mfma_f32_16x16x32_bf16 v[58:61], v[182:185], v[190:193], v[58:61]
	v_mfma_f32_16x16x32_bf16 v[58:61], v[168:171], v[186:189], v[58:61]
	v_mfma_f32_16x16x32_bf16 v[50:53], v[168:171], v[194:197], v[50:53]
	v_mfma_f32_16x16x32_bf16 v[50:53], v[182:185], v[198:201], v[50:53]
	v_mfma_f32_16x16x32_bf16 v[54:57], v[164:167], v[198:201], v[54:57]
	v_mfma_f32_16x16x32_bf16 v[54:57], v[146:149], v[194:197], v[54:57]
	v_mfma_f32_16x16x32_bf16 v[46:49], v[146:149], v[202:205], v[46:49]
	v_mfma_f32_16x16x32_bf16 v[46:49], v[164:167], v[206:209], v[46:49]
	v_mfma_f32_16x16x32_bf16 v[42:45], v[182:185], v[206:209], v[42:45]
	v_mfma_f32_16x16x32_bf16 v[42:45], v[168:171], v[202:205], v[42:45]
	v_mfma_f32_16x16x32_bf16 v[34:37], v[168:171], v[210:213], v[34:37]
	v_mfma_f32_16x16x32_bf16 v[34:37], v[182:185], v[214:217], v[34:37]
	v_mfma_f32_16x16x32_bf16 v[38:41], v[164:167], v[214:217], v[38:41]
	v_mfma_f32_16x16x32_bf16 v[38:41], v[146:149], v[210:213], v[38:41]
	s_barrier
	s_setprio 0
	s_mov_b32 m0, s23
	s_or_b32 s70, s69, 0x80
	ds_read_b128 v[186:189], v158 offset:49152
	ds_read_b128 v[190:193], v158 offset:50176
	ds_read_b128 v[194:197], v158 offset:51200
	ds_read_b128 v[198:201], v158 offset:52224
	ds_read_b128 v[202:205], v158 offset:53248
	ds_read_b128 v[206:209], v158 offset:54272
	ds_read_b128 v[210:213], v158 offset:55296
	ds_read_b128 v[214:217], v158 offset:56320
	buffer_load_dwordx4 v151, s[40:43], s70 offen lds
	s_mov_b32 m0, s24
	s_add_i32 s69, s69, 0x80080
	buffer_load_dwordx4 v153, s[40:43], s70 offen lds
	s_mov_b32 m0, s27
	s_nop 0
	buffer_load_dwordx4 v151, s[40:43], s69 offen lds
	s_mov_b32 m0, s28
	s_nop 0
	buffer_load_dwordx4 v153, s[40:43], s69 offen lds
	s_mov_b32 m0, s25
	s_nop 0
	buffer_load_dwordx4 v150, s[76:79], s68 offen lds
	s_mov_b32 m0, s26
	s_nop 0
	buffer_load_dwordx4 v152, s[76:79], s68 offen lds
	s_waitcnt vmcnt(8)
	s_waitcnt lgkmcnt(0)
	s_setprio 1
	s_barrier
	v_mfma_f32_16x16x32_bf16 v[94:97], v[130:133], v[186:189], v[94:97]
	v_mfma_f32_16x16x32_bf16 v[94:97], v[134:137], v[190:193], v[94:97]
	v_mfma_f32_16x16x32_bf16 v[90:93], v[142:145], v[190:193], v[90:93]
	v_mfma_f32_16x16x32_bf16 v[90:93], v[138:141], v[186:189], v[90:93]
	v_mfma_f32_16x16x32_bf16 v[82:85], v[138:141], v[194:197], v[82:85]
	v_mfma_f32_16x16x32_bf16 v[82:85], v[142:145], v[198:201], v[82:85]
	v_mfma_f32_16x16x32_bf16 v[86:89], v[134:137], v[198:201], v[86:89]
	v_mfma_f32_16x16x32_bf16 v[86:89], v[130:133], v[194:197], v[86:89]
	v_mfma_f32_16x16x32_bf16 v[78:81], v[130:133], v[202:205], v[78:81]
	v_mfma_f32_16x16x32_bf16 v[78:81], v[134:137], v[206:209], v[78:81]
	v_mfma_f32_16x16x32_bf16 v[74:77], v[142:145], v[206:209], v[74:77]
	v_mfma_f32_16x16x32_bf16 v[74:77], v[138:141], v[202:205], v[74:77]
	v_mfma_f32_16x16x32_bf16 v[66:69], v[138:141], v[210:213], v[66:69]
	v_mfma_f32_16x16x32_bf16 v[66:69], v[142:145], v[214:217], v[66:69]
	v_mfma_f32_16x16x32_bf16 v[70:73], v[134:137], v[214:217], v[70:73]
	v_mfma_f32_16x16x32_bf16 v[70:73], v[130:133], v[210:213], v[70:73]
	v_mfma_f32_16x16x32_bf16 v[30:33], v[146:149], v[186:189], v[30:33]
	v_mfma_f32_16x16x32_bf16 v[30:33], v[164:167], v[190:193], v[30:33]
	v_mfma_f32_16x16x32_bf16 v[26:29], v[182:185], v[190:193], v[26:29]
	v_mfma_f32_16x16x32_bf16 v[26:29], v[168:171], v[186:189], v[26:29]
	v_mfma_f32_16x16x32_bf16 v[18:21], v[168:171], v[194:197], v[18:21]
	v_mfma_f32_16x16x32_bf16 v[18:21], v[182:185], v[198:201], v[18:21]
	v_mfma_f32_16x16x32_bf16 v[22:25], v[164:167], v[198:201], v[22:25]
	v_mfma_f32_16x16x32_bf16 v[22:25], v[146:149], v[194:197], v[22:25]
	v_mfma_f32_16x16x32_bf16 v[14:17], v[146:149], v[202:205], v[14:17]
	v_mfma_f32_16x16x32_bf16 v[14:17], v[164:167], v[206:209], v[14:17]
	v_mfma_f32_16x16x32_bf16 v[10:13], v[182:185], v[206:209], v[10:13]
	v_mfma_f32_16x16x32_bf16 v[10:13], v[168:171], v[202:205], v[10:13]
	v_mfma_f32_16x16x32_bf16 v[2:5], v[168:171], v[210:213], v[2:5]
	v_mfma_f32_16x16x32_bf16 v[2:5], v[182:185], v[214:217], v[2:5]
	v_mfma_f32_16x16x32_bf16 v[6:9], v[164:167], v[214:217], v[6:9]
	v_mfma_f32_16x16x32_bf16 v[6:9], v[146:149], v[210:213], v[6:9]
	s_barrier
	s_setprio 0
	s_add_i32 s67, s67, 2
	s_addk_i32 s62, 0x100
	s_addk_i32 s63, 0x100
	.p2align	6

; #define PG8_STAGEX(rs, bufoff, soff, voff) do { _Pragma("unroll") for (int _i = 0; _i < 2; ++_i) \
;         __builtin_amdgcn_raw_ptr_buffer_load_lds(rs, (LAS unsigned*)(lds + (bufoff) + ldsw + _i * 8192), 16, (voff)[_i], (soff), 0, 0); } while (0)
; #define PG8_LDA(dst, b, h) do { _Pragma("unroll") for (int m = 0; m < 4; ++m) _Pragma("unroll") for (int k = 0; k < 2; ++k) dst[m][k] = *(const LAS bf16x8*)(lds + PG8_SA(b, h) + aoff + m * 2048 + k * 1024); } while (0)
; #define PG8_LDB(dst, b, h) do { _Pragma("unroll") for (int n = 0; n < 2; ++n) _Pragma("unroll") for (int k = 0; k < 2; ++k) dst[n][k] = *(const LAS bf16x8*)(lds + PG8_SB(b, h) + boff + n * 2048 + k * 1024); } while (0)
; #define PG8_WAIT_V(n) asm volatile("s_waitcnt vmcnt(" #n ")" ::: "memory")
; #define PG8_WAIT_L(n) asm volatile("s_waitcnt lgkmcnt(" #n ")" ::: "memory")
; #define PG8_BAR __builtin_amdgcn_s_barrier()
; #define PG8_SCHED __builtin_amdgcn_sched_barrier(0)
;     ...
;         for (int t = 0; t < nt; t += 2) {
;             const bool last = (t == nt - 2);
;             const unsigned a1 = cA + (unsigned)(t + 1) * kstep;
;             const unsigned a2 = last ? nA : cA + (unsigned)(t + 2) * kstep, b2 = last ? nB : cB + (unsigned)(t + 2) * kstep;
;             const unsigned a3 = a2 + kstep, b3 = b2 + kstep;
;             PG8_LDB(B0, 0, 0); PG8_LDB(B1, 0, 1); PG8_SCHED; PG8_LDA(At, 0, 0); PG8_STAGEX(rsA, PG8_SA(1, 1), a1 + hstepA, voffA);
;             PG8_WAIT_V(8); PG8_WAIT_L(0); PG8_BAR; PG8_MMA(0, 0, At, B0); PG8_MMA(0, 1, At, B1); PG8_BAR; PG8_SCHED;
;             PG8_LDA(At, 0, 1); PG8_STAGEX(rsB, PG8_SB(0, 0), b2, voffB); PG8_STAGEX(rsB, PG8_SB(0, 1), b2 + hstepB, voffB); PG8_STAGEX(rsA, PG8_SA(0, 0), a2, voffA);
;             PG8_WAIT_V(8); PG8_WAIT_L(0); PG8_BAR; PG8_MMA(1, 0, At, B0); PG8_MMA(1, 1, At, B1); PG8_BAR; PG8_SCHED;
.LBB0_1528:
	s_lshl_b32 s86, s65, 20
	s_and_b64 s[30:31], s[60:61], exec
	s_cselect_b32 s30, s86, s59
	s_lshl_b32 s87, s47, 20
	s_mov_b32 s84, s47
	s_and_b64 s[46:47], s[60:61], exec
	s_waitcnt lgkmcnt(0)
	s_waitcnt vmcnt(15)
	s_mov_b32 s85, s65
	s_cselect_b32 s31, s87, s63
	s_add_i32 s59, s59, 0x80080
	s_addk_i32 s63, 0x100
	s_mov_b32 s64, -2
	v_add_u32_e32 v118, 0x10000, v210
	v_add_u32_e32 v142, 0x14000, v210
	ds_read_b128 v[106:109], v118
	ds_read_b128 v[110:113], v118 offset:1024
	ds_read_b128 v[114:117], v118 offset:2048
	ds_read_b128 v[118:121], v118 offset:3072
	ds_read_b128 v[122:125], v142
	ds_read_b128 v[126:129], v142 offset:1024
	ds_read_b128 v[130:133], v142 offset:2048
	ds_read_b128 v[142:145], v142 offset:3072
	s_add_i32 s46, s59, 0xfff80080
	s_cmp_eq_u32 s64, 28
	s_cselect_b32 s67, s30, s46
	s_cselect_b32 s66, s31, s63
	s_or_b32 s65, s67, 0x80
	s_mov_b32 m0, s76
	ds_read_b128 v[164:167], v211
	ds_read_b128 v[168:171], v211 offset:1024
	ds_read_b128 v[182:185], v211 offset:2048
	ds_read_b128 v[186:189], v211 offset:3072
	ds_read_b128 v[190:193], v211 offset:4096
	ds_read_b128 v[194:197], v211 offset:5120
	ds_read_b128 v[198:201], v211 offset:6144
	ds_read_b128 v[202:205], v211 offset:7168
	buffer_load_dwordx4 v178, s[40:43], s59 offen lds
	s_mov_b32 m0, s77
	s_nop 0
	buffer_load_dwordx4 v206, s[40:43], s59 offen lds
	s_waitcnt vmcnt(8)
	s_waitcnt lgkmcnt(0)
	s_setprio 1
	s_barrier
	v_mfma_f32_16x16x32_bf16 v[158:161], v[106:109], v[164:167], 0
	v_mfma_f32_16x16x32_bf16 v[158:161], v[110:113], v[168:171], v[158:161]
	v_mfma_f32_16x16x32_bf16 v[154:157], v[118:121], v[168:171], 0
	v_mfma_f32_16x16x32_bf16 v[154:157], v[114:117], v[164:167], v[154:157]
	v_mfma_f32_16x16x32_bf16 v[146:149], v[114:117], v[182:185], 0
	v_mfma_f32_16x16x32_bf16 v[146:149], v[118:121], v[186:189], v[146:149]
	v_mfma_f32_16x16x32_bf16 v[150:153], v[110:113], v[186:189], 0
	v_mfma_f32_16x16x32_bf16 v[150:153], v[106:109], v[182:185], v[150:153]
	v_mfma_f32_16x16x32_bf16 v[138:141], v[106:109], v[190:193], 0
	v_mfma_f32_16x16x32_bf16 v[138:141], v[110:113], v[194:197], v[138:141]
	v_mfma_f32_16x16x32_bf16 v[134:137], v[118:121], v[194:197], 0
	v_mfma_f32_16x16x32_bf16 v[134:137], v[114:117], v[190:193], v[134:137]
	v_mfma_f32_16x16x32_bf16 v[98:101], v[114:117], v[198:201], 0
	v_mfma_f32_16x16x32_bf16 v[98:101], v[118:121], v[202:205], v[98:101]
	v_mfma_f32_16x16x32_bf16 v[102:105], v[110:113], v[202:205], 0
	v_mfma_f32_16x16x32_bf16 v[102:105], v[106:109], v[198:201], v[102:105]
	v_mfma_f32_16x16x32_bf16 v[62:65], v[122:125], v[164:167], 0
	v_mfma_f32_16x16x32_bf16 v[62:65], v[126:129], v[168:171], v[62:65]
	v_mfma_f32_16x16x32_bf16 v[58:61], v[142:145], v[168:171], 0
	v_mfma_f32_16x16x32_bf16 v[58:61], v[130:133], v[164:167], v[58:61]
	v_mfma_f32_16x16x32_bf16 v[50:53], v[130:133], v[182:185], 0
	v_mfma_f32_16x16x32_bf16 v[50:53], v[142:145], v[186:189], v[50:53]
	v_mfma_f32_16x16x32_bf16 v[54:57], v[126:129], v[186:189], 0
	v_mfma_f32_16x16x32_bf16 v[54:57], v[122:125], v[182:185], v[54:57]
	v_mfma_f32_16x16x32_bf16 v[46:49], v[122:125], v[190:193], 0
	v_mfma_f32_16x16x32_bf16 v[46:49], v[126:129], v[194:197], v[46:49]
	v_mfma_f32_16x16x32_bf16 v[42:45], v[142:145], v[194:197], 0
	v_mfma_f32_16x16x32_bf16 v[42:45], v[130:133], v[190:193], v[42:45]
	v_mfma_f32_16x16x32_bf16 v[34:37], v[130:133], v[198:201], 0
	v_mfma_f32_16x16x32_bf16 v[34:37], v[142:145], v[202:205], v[34:37]
	v_mfma_f32_16x16x32_bf16 v[38:41], v[126:129], v[202:205], 0
	v_mfma_f32_16x16x32_bf16 v[38:41], v[122:125], v[198:201], v[38:41]
	s_barrier
	s_setprio 0
	s_mov_b32 m0, s17
	s_mov_b32 s46, s42
	s_mov_b32 s47, s43
	ds_read_b128 v[164:167], v211 offset:16384
	ds_read_b128 v[168:171], v211 offset:17408
	ds_read_b128 v[182:185], v211 offset:18432
	ds_read_b128 v[186:189], v211 offset:19456
	ds_read_b128 v[190:193], v211 offset:20480
	ds_read_b128 v[194:197], v211 offset:21504
	ds_read_b128 v[198:201], v211 offset:22528
	ds_read_b128 v[202:205], v211 offset:23552
	buffer_load_dwordx4 v179, s[44:47], s66 offen lds
	s_mov_b32 m0, s18
	s_add_i32 s68, s66, 0x80000
	buffer_load_dwordx4 v207, s[44:47], s66 offen lds
	s_mov_b32 m0, s19
	s_nop 0
	buffer_load_dwordx4 v179, s[44:47], s68 offen lds
	s_mov_b32 m0, s20
	s_nop 0
	buffer_load_dwordx4 v207, s[44:47], s68 offen lds
	s_mov_b32 m0, s16
	s_nop 0
	buffer_load_dwordx4 v178, s[40:43], s67 offen lds
	s_mov_b32 m0, s21
	s_nop 0
	buffer_load_dwordx4 v206, s[40:43], s67 offen lds
	s_waitcnt vmcnt(8)
	s_waitcnt lgkmcnt(0)
	s_setprio 1
	s_barrier
	v_mfma_f32_16x16x32_bf16 v[94:97], v[106:109], v[164:167], 0
	v_mfma_f32_16x16x32_bf16 v[94:97], v[110:113], v[168:171], v[94:97]
	v_mfma_f32_16x16x32_bf16 v[90:93], v[118:121], v[168:171], 0
	v_mfma_f32_16x16x32_bf16 v[90:93], v[114:117], v[164:167], v[90:93]
	v_mfma_f32_16x16x32_bf16 v[82:85], v[114:117], v[182:185], 0
	v_mfma_f32_16x16x32_bf16 v[82:85], v[118:121], v[186:189], v[82:85]
	v_mfma_f32_16x16x32_bf16 v[86:89], v[110:113], v[186:189], 0
	v_mfma_f32_16x16x32_bf16 v[86:89], v[106:109], v[182:185], v[86:89]
	v_mfma_f32_16x16x32_bf16 v[78:81], v[106:109], v[190:193], 0
	v_mfma_f32_16x16x32_bf16 v[78:81], v[110:113], v[194:197], v[78:81]
	v_mfma_f32_16x16x32_bf16 v[74:77], v[118:121], v[194:197], 0
	v_mfma_f32_16x16x32_bf16 v[74:77], v[114:117], v[190:193], v[74:77]
	v_mfma_f32_16x16x32_bf16 v[66:69], v[114:117], v[198:201], 0
	v_mfma_f32_16x16x32_bf16 v[66:69], v[118:121], v[202:205], v[66:69]
	v_mfma_f32_16x16x32_bf16 v[70:73], v[110:113], v[202:205], 0
	v_mfma_f32_16x16x32_bf16 v[70:73], v[106:109], v[198:201], v[70:73]
	v_mfma_f32_16x16x32_bf16 v[30:33], v[122:125], v[164:167], 0
	v_mfma_f32_16x16x32_bf16 v[30:33], v[126:129], v[168:171], v[30:33]
	v_mfma_f32_16x16x32_bf16 v[26:29], v[142:145], v[168:171], 0
	v_mfma_f32_16x16x32_bf16 v[26:29], v[130:133], v[164:167], v[26:29]
	v_mfma_f32_16x16x32_bf16 v[18:21], v[130:133], v[182:185], 0
	v_mfma_f32_16x16x32_bf16 v[18:21], v[142:145], v[186:189], v[18:21]
	v_mfma_f32_16x16x32_bf16 v[22:25], v[126:129], v[186:189], 0
	v_mfma_f32_16x16x32_bf16 v[22:25], v[122:125], v[182:185], v[22:25]
	v_mfma_f32_16x16x32_bf16 v[14:17], v[122:125], v[190:193], 0
	v_mfma_f32_16x16x32_bf16 v[14:17], v[126:129], v[194:197], v[14:17]
	v_mfma_f32_16x16x32_bf16 v[10:13], v[142:145], v[194:197], 0
	v_mfma_f32_16x16x32_bf16 v[10:13], v[130:133], v[190:193], v[10:13]
	v_mfma_f32_16x16x32_bf16 v[2:5], v[130:133], v[198:201], 0
	v_mfma_f32_16x16x32_bf16 v[2:5], v[142:145], v[202:205], v[2:5]
	v_mfma_f32_16x16x32_bf16 v[6:9], v[126:129], v[202:205], 0
	v_mfma_f32_16x16x32_bf16 v[6:9], v[122:125], v[198:201], v[6:9]
	s_barrier
; #define PG8_STAGEX(rs, bufoff, soff, voff) do { _Pragma("unroll") for (int _i = 0; _i < 2; ++_i) \
;         __builtin_amdgcn_raw_ptr_buffer_load_lds(rs, (LAS unsigned*)(lds + (bufoff) + ldsw + _i * 8192), 16, (voff)[_i], (soff), 0, 0); } while (0)
; #define PG8_LDA(dst, b, h) do { _Pragma("unroll") for (int m = 0; m < 4; ++m) _Pragma("unroll") for (int k = 0; k < 2; ++k) dst[m][k] = *(const LAS bf16x8*)(lds + PG8_SA(b, h) + aoff + m * 2048 + k * 1024); } while (0)
; #define PG8_LDB(dst, b, h) do { _Pragma("unroll") for (int n = 0; n < 2; ++n) _Pragma("unroll") for (int k = 0; k < 2; ++k) dst[n][k] = *(const LAS bf16x8*)(lds + PG8_SB(b, h) + boff + n * 2048 + k * 1024); } while (0)
; #define PG8_WAIT_V(n) asm volatile("s_waitcnt vmcnt(" #n ")" ::: "memory")
; #define PG8_WAIT_L(n) asm volatile("s_waitcnt lgkmcnt(" #n ")" ::: "memory")
; #define PG8_BAR __builtin_amdgcn_s_barrier()
; #define PG8_SCHED __builtin_amdgcn_sched_barrier(0)
;     ...
;             PG8_LDB(B0, 1, 0); PG8_LDB(B1, 1, 1); PG8_SCHED; PG8_LDA(At, 1, 0); PG8_STAGEX(rsA, PG8_SA(0, 1), a2 + hstepA, voffA);
;             PG8_WAIT_V(8); PG8_WAIT_L(0); PG8_BAR; PG8_MMA(0, 0, At, B0); PG8_MMA(0, 1, At, B1); PG8_BAR; PG8_SCHED;
;             PG8_LDA(At, 1, 1); PG8_STAGEX(rsB, PG8_SB(1, 0), b3, voffB); PG8_STAGEX(rsB, PG8_SB(1, 1), b3 + hstepB, voffB); PG8_STAGEX(rsA, PG8_SA(1, 0), a3, voffA);
;             PG8_WAIT_V(8); PG8_WAIT_L(0); PG8_BAR; PG8_MMA(1, 0, At, B0); PG8_MMA(1, 1, At, B1); PG8_BAR; PG8_SCHED;
	s_setprio 0
	v_add_u32_e32 v118, 0x18000, v210
	v_add_u32_e32 v142, 0x1c000, v210
	ds_read_b128 v[106:109], v118
	ds_read_b128 v[110:113], v118 offset:1024
	ds_read_b128 v[114:117], v118 offset:2048
	ds_read_b128 v[118:121], v118 offset:3072
	ds_read_b128 v[122:125], v142
	ds_read_b128 v[126:129], v142 offset:1024
	ds_read_b128 v[130:133], v142 offset:2048
	ds_read_b128 v[142:145], v142 offset:3072
	s_add_i32 s67, s67, 0x80000
	s_mov_b32 m0, s22
	ds_read_b128 v[164:167], v211 offset:32768
	ds_read_b128 v[168:171], v211 offset:33792
	ds_read_b128 v[182:185], v211 offset:34816
	ds_read_b128 v[186:189], v211 offset:35840
	ds_read_b128 v[190:193], v211 offset:36864
	ds_read_b128 v[194:197], v211 offset:37888
	ds_read_b128 v[198:201], v211 offset:38912
	ds_read_b128 v[202:205], v211 offset:39936
	buffer_load_dwordx4 v178, s[40:43], s67 offen lds
	s_mov_b32 m0, s23
	s_nop 0
	buffer_load_dwordx4 v206, s[40:43], s67 offen lds
	s_waitcnt vmcnt(8)
	s_waitcnt lgkmcnt(0)
	s_setprio 1
	s_barrier
	v_mfma_f32_16x16x32_bf16 v[158:161], v[106:109], v[164:167], v[158:161]
	v_mfma_f32_16x16x32_bf16 v[158:161], v[110:113], v[168:171], v[158:161]
	v_mfma_f32_16x16x32_bf16 v[154:157], v[118:121], v[168:171], v[154:157]
	v_mfma_f32_16x16x32_bf16 v[154:157], v[114:117], v[164:167], v[154:157]
	v_mfma_f32_16x16x32_bf16 v[146:149], v[114:117], v[182:185], v[146:149]
	v_mfma_f32_16x16x32_bf16 v[146:149], v[118:121], v[186:189], v[146:149]
	v_mfma_f32_16x16x32_bf16 v[150:153], v[110:113], v[186:189], v[150:153]
	v_mfma_f32_16x16x32_bf16 v[150:153], v[106:109], v[182:185], v[150:153]
	v_mfma_f32_16x16x32_bf16 v[138:141], v[106:109], v[190:193], v[138:141]
	v_mfma_f32_16x16x32_bf16 v[138:141], v[110:113], v[194:197], v[138:141]
	v_mfma_f32_16x16x32_bf16 v[134:137], v[118:121], v[194:197], v[134:137]
	v_mfma_f32_16x16x32_bf16 v[134:137], v[114:117], v[190:193], v[134:137]
	v_mfma_f32_16x16x32_bf16 v[98:101], v[114:117], v[198:201], v[98:101]
	v_mfma_f32_16x16x32_bf16 v[98:101], v[118:121], v[202:205], v[98:101]
	v_mfma_f32_16x16x32_bf16 v[102:105], v[110:113], v[202:205], v[102:105]
	v_mfma_f32_16x16x32_bf16 v[102:105], v[106:109], v[198:201], v[102:105]
	v_mfma_f32_16x16x32_bf16 v[62:65], v[122:125], v[164:167], v[62:65]
	v_mfma_f32_16x16x32_bf16 v[62:65], v[126:129], v[168:171], v[62:65]
	v_mfma_f32_16x16x32_bf16 v[58:61], v[142:145], v[168:171], v[58:61]
	v_mfma_f32_16x16x32_bf16 v[58:61], v[130:133], v[164:167], v[58:61]
	v_mfma_f32_16x16x32_bf16 v[50:53], v[130:133], v[182:185], v[50:53]
	v_mfma_f32_16x16x32_bf16 v[50:53], v[142:145], v[186:189], v[50:53]
	v_mfma_f32_16x16x32_bf16 v[54:57], v[126:129], v[186:189], v[54:57]
	v_mfma_f32_16x16x32_bf16 v[54:57], v[122:125], v[182:185], v[54:57]
	v_mfma_f32_16x16x32_bf16 v[46:49], v[122:125], v[190:193], v[46:49]
	v_mfma_f32_16x16x32_bf16 v[46:49], v[126:129], v[194:197], v[46:49]
	v_mfma_f32_16x16x32_bf16 v[42:45], v[142:145], v[194:197], v[42:45]
	v_mfma_f32_16x16x32_bf16 v[42:45], v[130:133], v[190:193], v[42:45]
	v_mfma_f32_16x16x32_bf16 v[34:37], v[130:133], v[198:201], v[34:37]
	v_mfma_f32_16x16x32_bf16 v[34:37], v[142:145], v[202:205], v[34:37]
	v_mfma_f32_16x16x32_bf16 v[38:41], v[126:129], v[202:205], v[38:41]
	v_mfma_f32_16x16x32_bf16 v[38:41], v[122:125], v[198:201], v[38:41]
	s_barrier
	s_setprio 0
	s_mov_b32 m0, s54
	s_or_b32 s67, s66, 0x80
	ds_read_b128 v[164:167], v211 offset:49152
	ds_read_b128 v[168:171], v211 offset:50176
	ds_read_b128 v[182:185], v211 offset:51200
	ds_read_b128 v[186:189], v211 offset:52224
	ds_read_b128 v[190:193], v211 offset:53248
	ds_read_b128 v[194:197], v211 offset:54272
	ds_read_b128 v[198:201], v211 offset:55296
	ds_read_b128 v[202:205], v211 offset:56320
	buffer_load_dwordx4 v179, s[44:47], s67 offen lds
	s_mov_b32 m0, s55
	s_add_i32 s66, s66, 0x80080
	buffer_load_dwordx4 v207, s[44:47], s67 offen lds
	s_mov_b32 m0, s74
	s_nop 0
	buffer_load_dwordx4 v179, s[44:47], s66 offen lds
	s_mov_b32 m0, s75
	s_nop 0
	buffer_load_dwordx4 v207, s[44:47], s66 offen lds
	s_mov_b32 m0, s72
	s_nop 0
	buffer_load_dwordx4 v178, s[40:43], s65 offen lds
	s_mov_b32 m0, s73
	s_nop 0
	buffer_load_dwordx4 v206, s[40:43], s65 offen lds
	s_waitcnt vmcnt(8)
	s_waitcnt lgkmcnt(0)
	s_setprio 1
	s_barrier
	v_mfma_f32_16x16x32_bf16 v[94:97], v[106:109], v[164:167], v[94:97]
	v_mfma_f32_16x16x32_bf16 v[94:97], v[110:113], v[168:171], v[94:97]
	v_mfma_f32_16x16x32_bf16 v[90:93], v[118:121], v[168:171], v[90:93]
	v_mfma_f32_16x16x32_bf16 v[90:93], v[114:117], v[164:167], v[90:93]
	v_mfma_f32_16x16x32_bf16 v[82:85], v[114:117], v[182:185], v[82:85]
	v_mfma_f32_16x16x32_bf16 v[82:85], v[118:121], v[186:189], v[82:85]
	v_mfma_f32_16x16x32_bf16 v[86:89], v[110:113], v[186:189], v[86:89]
	v_mfma_f32_16x16x32_bf16 v[86:89], v[106:109], v[182:185], v[86:89]
	v_mfma_f32_16x16x32_bf16 v[78:81], v[106:109], v[190:193], v[78:81]
	v_mfma_f32_16x16x32_bf16 v[78:81], v[110:113], v[194:197], v[78:81]
	v_mfma_f32_16x16x32_bf16 v[74:77], v[118:121], v[194:197], v[74:77]
	v_mfma_f32_16x16x32_bf16 v[74:77], v[114:117], v[190:193], v[74:77]
	v_mfma_f32_16x16x32_bf16 v[66:69], v[114:117], v[198:201], v[66:69]
	v_mfma_f32_16x16x32_bf16 v[66:69], v[118:121], v[202:205], v[66:69]
	v_mfma_f32_16x16x32_bf16 v[70:73], v[110:113], v[202:205], v[70:73]
	v_mfma_f32_16x16x32_bf16 v[70:73], v[106:109], v[198:201], v[70:73]
	v_mfma_f32_16x16x32_bf16 v[30:33], v[122:125], v[164:167], v[30:33]
	v_mfma_f32_16x16x32_bf16 v[30:33], v[126:129], v[168:171], v[30:33]
	v_mfma_f32_16x16x32_bf16 v[26:29], v[142:145], v[168:171], v[26:29]
	v_mfma_f32_16x16x32_bf16 v[26:29], v[130:133], v[164:167], v[26:29]
	v_mfma_f32_16x16x32_bf16 v[18:21], v[130:133], v[182:185], v[18:21]
	v_mfma_f32_16x16x32_bf16 v[18:21], v[142:145], v[186:189], v[18:21]
	v_mfma_f32_16x16x32_bf16 v[22:25], v[126:129], v[186:189], v[22:25]
	v_mfma_f32_16x16x32_bf16 v[22:25], v[122:125], v[182:185], v[22:25]
	v_mfma_f32_16x16x32_bf16 v[14:17], v[122:125], v[190:193], v[14:17]
	v_mfma_f32_16x16x32_bf16 v[14:17], v[126:129], v[194:197], v[14:17]
	v_mfma_f32_16x16x32_bf16 v[10:13], v[142:145], v[194:197], v[10:13]
	v_mfma_f32_16x16x32_bf16 v[10:13], v[130:133], v[190:193], v[10:13]
	v_mfma_f32_16x16x32_bf16 v[2:5], v[130:133], v[198:201], v[2:5]
	v_mfma_f32_16x16x32_bf16 v[2:5], v[142:145], v[202:205], v[2:5]
	v_mfma_f32_16x16x32_bf16 v[6:9], v[126:129], v[202:205], v[6:9]
	v_mfma_f32_16x16x32_bf16 v[6:9], v[122:125], v[198:201], v[6:9]
	s_barrier
	s_setprio 0
	s_add_i32 s64, s64, 2
	s_addk_i32 s59, 0x100
	s_addk_i32 s63, 0x100
	.p2align	6

; #define PG8_STAGEX(rs, bufoff, soff, voff) do { _Pragma("unroll") for (int _i = 0; _i < 2; ++_i) \
;         __builtin_amdgcn_raw_ptr_buffer_load_lds(rs, (LAS unsigned*)(lds + (bufoff) + ldsw + _i * 8192), 16, (voff)[_i], (soff), 0, 0); } while (0)
; #define PG8_LDA(dst, b, h) do { _Pragma("unroll") for (int m = 0; m < 4; ++m) _Pragma("unroll") for (int k = 0; k < 2; ++k) dst[m][k] = *(const LAS bf16x8*)(lds + PG8_SA(b, h) + aoff + m * 2048 + k * 1024); } while (0)
; #define PG8_LDB(dst, b, h) do { _Pragma("unroll") for (int n = 0; n < 2; ++n) _Pragma("unroll") for (int k = 0; k < 2; ++k) dst[n][k] = *(const LAS bf16x8*)(lds + PG8_SB(b, h) + boff + n * 2048 + k * 1024); } while (0)
; #define PG8_WAIT_V(n) asm volatile("s_waitcnt vmcnt(" #n ")" ::: "memory")
; #define PG8_WAIT_L(n) asm volatile("s_waitcnt lgkmcnt(" #n ")" ::: "memory")
; #define PG8_BAR __builtin_amdgcn_s_barrier()
; #define PG8_SCHED __builtin_amdgcn_sched_barrier(0)
;     ...
;         for (int t = 0; t < nt; t += 2) {
;             const bool last = (t == nt - 2);
;             const unsigned a1 = cA + (unsigned)(t + 1) * kstep;
;             const unsigned a2 = last ? nA : cA + (unsigned)(t + 2) * kstep, b2 = last ? nB : cB + (unsigned)(t + 2) * kstep;
;             const unsigned a3 = a2 + kstep, b3 = b2 + kstep;
;             PG8_LDB(B0, 0, 0); PG8_LDB(B1, 0, 1); PG8_SCHED; PG8_LDA(At, 0, 0); PG8_STAGEX(rsA, PG8_SA(1, 1), a1 + hstepA, voffA);
;             PG8_WAIT_V(8); PG8_WAIT_L(0); PG8_BAR; PG8_MMA(0, 0, At, B0); PG8_MMA(0, 1, At, B1); PG8_BAR; PG8_SCHED;
;             PG8_LDA(At, 0, 1); PG8_STAGEX(rsB, PG8_SB(0, 0), b2, voffB); PG8_STAGEX(rsB, PG8_SB(0, 1), b2 + hstepB, voffB); PG8_STAGEX(rsA, PG8_SA(0, 0), a2, voffA);
;             PG8_WAIT_V(8); PG8_WAIT_L(0); PG8_BAR; PG8_MMA(1, 0, At, B0); PG8_MMA(1, 1, At, B1); PG8_BAR; PG8_SCHED;
.LBB0_1650:
	s_lshl_b32 s55, s54, 20
	s_and_b64 s[30:31], s[38:39], exec
	s_cselect_b32 s30, s55, s61
	s_lshl_b32 s58, s53, 20
	s_and_b64 s[42:43], s[38:39], exec
	s_waitcnt vmcnt(15)
	s_cselect_b32 s31, s58, s62
	s_add_i32 s61, s61, 0x80080
	s_addk_i32 s62, 0x100
	s_mov_b32 s63, -2
	v_add_u32_e32 v102, 0x10000, v172
	v_add_u32_e32 v146, 0x14000, v172
	ds_read_b128 v[82:85], v102
	ds_read_b128 v[86:89], v102 offset:1024
	ds_read_b128 v[98:101], v102 offset:2048
	ds_read_b128 v[102:105], v102 offset:3072
	ds_read_b128 v[150:153], v146
	ds_read_b128 v[154:157], v146 offset:1024
	ds_read_b128 v[182:185], v146 offset:2048
	ds_read_b128 v[186:189], v146 offset:3072
	s_add_i32 s42, s61, 0xfff80080
	s_cmp_eq_u32 s63, 28
	s_cselect_b32 s66, s30, s42
	s_cselect_b32 s65, s31, s62
	s_or_b32 s64, s66, 0x80
	s_mov_b32 m0, s29
	ds_read_b128 v[190:193], v173
	ds_read_b128 v[194:197], v173 offset:1024
	ds_read_b128 v[198:201], v173 offset:2048
	ds_read_b128 v[202:205], v173 offset:3072
	ds_read_b128 v[206:209], v173 offset:4096
	ds_read_b128 v[210:213], v173 offset:5120
	ds_read_b128 v[214:217], v173 offset:6144
	ds_read_b128 v[218:221], v173 offset:7168
	buffer_load_dwordx4 v159, s[76:79], s61 offen lds
	s_mov_b32 m0, s50
	s_nop 0
	buffer_load_dwordx4 v163, s[76:79], s61 offen lds
	s_waitcnt vmcnt(8)
	s_waitcnt lgkmcnt(0)
	s_setprio 1
	s_barrier
	v_mfma_f32_16x16x32_bf16 v[142:145], v[82:85], v[190:193], 0
	v_mfma_f32_16x16x32_bf16 v[142:145], v[86:89], v[194:197], v[142:145]
	v_mfma_f32_16x16x32_bf16 v[134:137], v[102:105], v[194:197], 0
	v_mfma_f32_16x16x32_bf16 v[134:137], v[98:101], v[190:193], v[134:137]
	v_mfma_f32_16x16x32_bf16 v[118:121], v[98:101], v[198:201], 0
	v_mfma_f32_16x16x32_bf16 v[118:121], v[102:105], v[202:205], v[118:121]
	v_mfma_f32_16x16x32_bf16 v[126:129], v[86:89], v[202:205], 0
	v_mfma_f32_16x16x32_bf16 v[126:129], v[82:85], v[198:201], v[126:129]
	v_mfma_f32_16x16x32_bf16 v[110:113], v[82:85], v[206:209], 0
	v_mfma_f32_16x16x32_bf16 v[110:113], v[86:89], v[210:213], v[110:113]
	v_mfma_f32_16x16x32_bf16 v[94:97], v[102:105], v[210:213], 0
	v_mfma_f32_16x16x32_bf16 v[94:97], v[98:101], v[206:209], v[94:97]
	v_mfma_f32_16x16x32_bf16 v[70:73], v[98:101], v[214:217], 0
	v_mfma_f32_16x16x32_bf16 v[70:73], v[102:105], v[218:221], v[70:73]
	v_mfma_f32_16x16x32_bf16 v[78:81], v[86:89], v[218:221], 0
	v_mfma_f32_16x16x32_bf16 v[78:81], v[82:85], v[214:217], v[78:81]
	v_mfma_f32_16x16x32_bf16 v[138:141], v[150:153], v[190:193], 0
	v_mfma_f32_16x16x32_bf16 v[138:141], v[154:157], v[194:197], v[138:141]
	v_mfma_f32_16x16x32_bf16 v[130:133], v[186:189], v[194:197], 0
	v_mfma_f32_16x16x32_bf16 v[130:133], v[182:185], v[190:193], v[130:133]
	v_mfma_f32_16x16x32_bf16 v[114:117], v[182:185], v[198:201], 0
	v_mfma_f32_16x16x32_bf16 v[114:117], v[186:189], v[202:205], v[114:117]
	v_mfma_f32_16x16x32_bf16 v[122:125], v[154:157], v[202:205], 0
	v_mfma_f32_16x16x32_bf16 v[122:125], v[150:153], v[198:201], v[122:125]
	v_mfma_f32_16x16x32_bf16 v[106:109], v[150:153], v[206:209], 0
	v_mfma_f32_16x16x32_bf16 v[106:109], v[154:157], v[210:213], v[106:109]
	v_mfma_f32_16x16x32_bf16 v[90:93], v[186:189], v[210:213], 0
	v_mfma_f32_16x16x32_bf16 v[90:93], v[182:185], v[206:209], v[90:93]
	v_mfma_f32_16x16x32_bf16 v[66:69], v[182:185], v[214:217], 0
	v_mfma_f32_16x16x32_bf16 v[66:69], v[186:189], v[218:221], v[66:69]
	v_mfma_f32_16x16x32_bf16 v[74:77], v[154:157], v[218:221], 0
	v_mfma_f32_16x16x32_bf16 v[74:77], v[150:153], v[214:217], v[74:77]
	s_barrier
	s_setprio 0
	s_mov_b32 m0, s16
	s_mov_b32 s42, s78
	s_mov_b32 s43, s79
	ds_read_b128 v[190:193], v173 offset:16384
	ds_read_b128 v[194:197], v173 offset:17408
	ds_read_b128 v[198:201], v173 offset:18432
	ds_read_b128 v[202:205], v173 offset:19456
	ds_read_b128 v[206:209], v173 offset:20480
	ds_read_b128 v[210:213], v173 offset:21504
	ds_read_b128 v[214:217], v173 offset:22528
	ds_read_b128 v[218:221], v173 offset:23552
	buffer_load_dwordx4 v161, s[40:43], s65 offen lds
	s_mov_b32 m0, s17
	s_add_i32 s67, s65, 0x80000
	buffer_load_dwordx4 v165, s[40:43], s65 offen lds
	s_mov_b32 m0, s18
	s_nop 0
	buffer_load_dwordx4 v161, s[40:43], s67 offen lds
	s_mov_b32 m0, s19
	s_nop 0
	buffer_load_dwordx4 v165, s[40:43], s67 offen lds
	s_mov_b32 m0, s15
	s_nop 0
	buffer_load_dwordx4 v159, s[76:79], s66 offen lds
	s_mov_b32 m0, s20
	s_nop 0
	buffer_load_dwordx4 v163, s[76:79], s66 offen lds
	s_waitcnt vmcnt(8)
	s_waitcnt lgkmcnt(0)
	s_setprio 1
	s_barrier
	v_mfma_f32_16x16x32_bf16 v[62:65], v[82:85], v[190:193], 0
	v_mfma_f32_16x16x32_bf16 v[62:65], v[86:89], v[194:197], v[62:65]
	v_mfma_f32_16x16x32_bf16 v[54:57], v[102:105], v[194:197], 0
	v_mfma_f32_16x16x32_bf16 v[54:57], v[98:101], v[190:193], v[54:57]
	v_mfma_f32_16x16x32_bf16 v[38:41], v[98:101], v[198:201], 0
	v_mfma_f32_16x16x32_bf16 v[38:41], v[102:105], v[202:205], v[38:41]
	v_mfma_f32_16x16x32_bf16 v[46:49], v[86:89], v[202:205], 0
	v_mfma_f32_16x16x32_bf16 v[46:49], v[82:85], v[198:201], v[46:49]
	v_mfma_f32_16x16x32_bf16 v[30:33], v[82:85], v[206:209], 0
	v_mfma_f32_16x16x32_bf16 v[30:33], v[86:89], v[210:213], v[30:33]
	v_mfma_f32_16x16x32_bf16 v[22:25], v[102:105], v[210:213], 0
	v_mfma_f32_16x16x32_bf16 v[22:25], v[98:101], v[206:209], v[22:25]
	v_mfma_f32_16x16x32_bf16 v[6:9], v[98:101], v[214:217], 0
	v_mfma_f32_16x16x32_bf16 v[6:9], v[102:105], v[218:221], v[6:9]
	v_mfma_f32_16x16x32_bf16 v[14:17], v[86:89], v[218:221], 0
	v_mfma_f32_16x16x32_bf16 v[14:17], v[82:85], v[214:217], v[14:17]
	v_mfma_f32_16x16x32_bf16 v[58:61], v[150:153], v[190:193], 0
	v_mfma_f32_16x16x32_bf16 v[58:61], v[154:157], v[194:197], v[58:61]
	v_mfma_f32_16x16x32_bf16 v[50:53], v[186:189], v[194:197], 0
	v_mfma_f32_16x16x32_bf16 v[50:53], v[182:185], v[190:193], v[50:53]
	v_mfma_f32_16x16x32_bf16 v[34:37], v[182:185], v[198:201], 0
	v_mfma_f32_16x16x32_bf16 v[34:37], v[186:189], v[202:205], v[34:37]
	v_mfma_f32_16x16x32_bf16 v[42:45], v[154:157], v[202:205], 0
	v_mfma_f32_16x16x32_bf16 v[42:45], v[150:153], v[198:201], v[42:45]
	v_mfma_f32_16x16x32_bf16 v[26:29], v[150:153], v[206:209], 0
	v_mfma_f32_16x16x32_bf16 v[26:29], v[154:157], v[210:213], v[26:29]
	v_mfma_f32_16x16x32_bf16 v[18:21], v[186:189], v[210:213], 0
	v_mfma_f32_16x16x32_bf16 v[18:21], v[182:185], v[206:209], v[18:21]
	v_mfma_f32_16x16x32_bf16 v[2:5], v[182:185], v[214:217], 0
	v_mfma_f32_16x16x32_bf16 v[2:5], v[186:189], v[218:221], v[2:5]
	v_mfma_f32_16x16x32_bf16 v[10:13], v[154:157], v[218:221], 0
	v_mfma_f32_16x16x32_bf16 v[10:13], v[150:153], v[214:217], v[10:13]
	s_barrier
; #define PG8_STAGEX(rs, bufoff, soff, voff) do { _Pragma("unroll") for (int _i = 0; _i < 2; ++_i) \
;         __builtin_amdgcn_raw_ptr_buffer_load_lds(rs, (LAS unsigned*)(lds + (bufoff) + ldsw + _i * 8192), 16, (voff)[_i], (soff), 0, 0); } while (0)
; #define PG8_LDA(dst, b, h) do { _Pragma("unroll") for (int m = 0; m < 4; ++m) _Pragma("unroll") for (int k = 0; k < 2; ++k) dst[m][k] = *(const LAS bf16x8*)(lds + PG8_SA(b, h) + aoff + m * 2048 + k * 1024); } while (0)
; #define PG8_LDB(dst, b, h) do { _Pragma("unroll") for (int n = 0; n < 2; ++n) _Pragma("unroll") for (int k = 0; k < 2; ++k) dst[n][k] = *(const LAS bf16x8*)(lds + PG8_SB(b, h) + boff + n * 2048 + k * 1024); } while (0)
; #define PG8_WAIT_V(n) asm volatile("s_waitcnt vmcnt(" #n ")" ::: "memory")
; #define PG8_WAIT_L(n) asm volatile("s_waitcnt lgkmcnt(" #n ")" ::: "memory")
; #define PG8_BAR __builtin_amdgcn_s_barrier()
; #define PG8_SCHED __builtin_amdgcn_sched_barrier(0)
;     ...
;             PG8_LDB(B0, 1, 0); PG8_LDB(B1, 1, 1); PG8_SCHED; PG8_LDA(At, 1, 0); PG8_STAGEX(rsA, PG8_SA(0, 1), a2 + hstepA, voffA);
;             PG8_WAIT_V(8); PG8_WAIT_L(0); PG8_BAR; PG8_MMA(0, 0, At, B0); PG8_MMA(0, 1, At, B1); PG8_BAR; PG8_SCHED;
;             PG8_LDA(At, 1, 1); PG8_STAGEX(rsB, PG8_SB(1, 0), b3, voffB); PG8_STAGEX(rsB, PG8_SB(1, 1), b3 + hstepB, voffB); PG8_STAGEX(rsA, PG8_SA(1, 0), a3, voffA);
;             PG8_WAIT_V(8); PG8_WAIT_L(0); PG8_BAR; PG8_MMA(1, 0, At, B0); PG8_MMA(1, 1, At, B1); PG8_BAR; PG8_SCHED;
	s_setprio 0
	v_add_u32_e32 v102, 0x18000, v172
	v_add_u32_e32 v146, 0x1c000, v172
	ds_read_b128 v[82:85], v102
	ds_read_b128 v[86:89], v102 offset:1024
	ds_read_b128 v[98:101], v102 offset:2048
	ds_read_b128 v[102:105], v102 offset:3072
	ds_read_b128 v[150:153], v146
	ds_read_b128 v[154:157], v146 offset:1024
	ds_read_b128 v[182:185], v146 offset:2048
	ds_read_b128 v[186:189], v146 offset:3072
	s_add_i32 s66, s66, 0x80000
	s_mov_b32 m0, s21
	ds_read_b128 v[190:193], v173 offset:32768
	ds_read_b128 v[194:197], v173 offset:33792
	ds_read_b128 v[198:201], v173 offset:34816
	ds_read_b128 v[202:205], v173 offset:35840
	ds_read_b128 v[206:209], v173 offset:36864
	ds_read_b128 v[210:213], v173 offset:37888
	ds_read_b128 v[214:217], v173 offset:38912
	ds_read_b128 v[218:221], v173 offset:39936
	buffer_load_dwordx4 v159, s[76:79], s66 offen lds
	s_mov_b32 m0, s22
	s_nop 0
	buffer_load_dwordx4 v163, s[76:79], s66 offen lds
	s_waitcnt vmcnt(8)
	s_waitcnt lgkmcnt(0)
	s_setprio 1
	s_barrier
	v_mfma_f32_16x16x32_bf16 v[142:145], v[82:85], v[190:193], v[142:145]
	v_mfma_f32_16x16x32_bf16 v[142:145], v[86:89], v[194:197], v[142:145]
	v_mfma_f32_16x16x32_bf16 v[134:137], v[102:105], v[194:197], v[134:137]
	v_mfma_f32_16x16x32_bf16 v[134:137], v[98:101], v[190:193], v[134:137]
	v_mfma_f32_16x16x32_bf16 v[118:121], v[98:101], v[198:201], v[118:121]
	v_mfma_f32_16x16x32_bf16 v[118:121], v[102:105], v[202:205], v[118:121]
	v_mfma_f32_16x16x32_bf16 v[126:129], v[86:89], v[202:205], v[126:129]
	v_mfma_f32_16x16x32_bf16 v[126:129], v[82:85], v[198:201], v[126:129]
	v_mfma_f32_16x16x32_bf16 v[110:113], v[82:85], v[206:209], v[110:113]
	v_mfma_f32_16x16x32_bf16 v[110:113], v[86:89], v[210:213], v[110:113]
	v_mfma_f32_16x16x32_bf16 v[94:97], v[102:105], v[210:213], v[94:97]
	v_mfma_f32_16x16x32_bf16 v[94:97], v[98:101], v[206:209], v[94:97]
	v_mfma_f32_16x16x32_bf16 v[70:73], v[98:101], v[214:217], v[70:73]
	v_mfma_f32_16x16x32_bf16 v[70:73], v[102:105], v[218:221], v[70:73]
	v_mfma_f32_16x16x32_bf16 v[78:81], v[86:89], v[218:221], v[78:81]
	v_mfma_f32_16x16x32_bf16 v[78:81], v[82:85], v[214:217], v[78:81]
	v_mfma_f32_16x16x32_bf16 v[138:141], v[150:153], v[190:193], v[138:141]
	v_mfma_f32_16x16x32_bf16 v[138:141], v[154:157], v[194:197], v[138:141]
	v_mfma_f32_16x16x32_bf16 v[130:133], v[186:189], v[194:197], v[130:133]
	v_mfma_f32_16x16x32_bf16 v[130:133], v[182:185], v[190:193], v[130:133]
	v_mfma_f32_16x16x32_bf16 v[114:117], v[182:185], v[198:201], v[114:117]
	v_mfma_f32_16x16x32_bf16 v[114:117], v[186:189], v[202:205], v[114:117]
	v_mfma_f32_16x16x32_bf16 v[122:125], v[154:157], v[202:205], v[122:125]
	v_mfma_f32_16x16x32_bf16 v[122:125], v[150:153], v[198:201], v[122:125]
	v_mfma_f32_16x16x32_bf16 v[106:109], v[150:153], v[206:209], v[106:109]
	v_mfma_f32_16x16x32_bf16 v[106:109], v[154:157], v[210:213], v[106:109]
	v_mfma_f32_16x16x32_bf16 v[90:93], v[186:189], v[210:213], v[90:93]
	v_mfma_f32_16x16x32_bf16 v[90:93], v[182:185], v[206:209], v[90:93]
	v_mfma_f32_16x16x32_bf16 v[66:69], v[182:185], v[214:217], v[66:69]
	v_mfma_f32_16x16x32_bf16 v[66:69], v[186:189], v[218:221], v[66:69]
	v_mfma_f32_16x16x32_bf16 v[74:77], v[154:157], v[218:221], v[74:77]
	v_mfma_f32_16x16x32_bf16 v[74:77], v[150:153], v[214:217], v[74:77]
	s_barrier
	s_setprio 0
	s_mov_b32 m0, s23
	s_or_b32 s66, s65, 0x80
	ds_read_b128 v[190:193], v173 offset:49152
	ds_read_b128 v[194:197], v173 offset:50176
	ds_read_b128 v[198:201], v173 offset:51200
	ds_read_b128 v[202:205], v173 offset:52224
	ds_read_b128 v[206:209], v173 offset:53248
	ds_read_b128 v[210:213], v173 offset:54272
	ds_read_b128 v[214:217], v173 offset:55296
	ds_read_b128 v[218:221], v173 offset:56320
	buffer_load_dwordx4 v161, s[40:43], s66 offen lds
	s_mov_b32 m0, s24
	s_add_i32 s65, s65, 0x80080
	buffer_load_dwordx4 v165, s[40:43], s66 offen lds
	s_mov_b32 m0, s27
	s_nop 0
	buffer_load_dwordx4 v161, s[40:43], s65 offen lds
	s_mov_b32 m0, s28
	s_nop 0
	buffer_load_dwordx4 v165, s[40:43], s65 offen lds
	s_mov_b32 m0, s25
	s_nop 0
	buffer_load_dwordx4 v159, s[76:79], s64 offen lds
	s_mov_b32 m0, s26
	s_nop 0
	buffer_load_dwordx4 v163, s[76:79], s64 offen lds
	s_waitcnt vmcnt(8)
	s_waitcnt lgkmcnt(0)
	s_setprio 1
	s_barrier
	v_mfma_f32_16x16x32_bf16 v[62:65], v[82:85], v[190:193], v[62:65]
	v_mfma_f32_16x16x32_bf16 v[62:65], v[86:89], v[194:197], v[62:65]
	v_mfma_f32_16x16x32_bf16 v[54:57], v[102:105], v[194:197], v[54:57]
	v_mfma_f32_16x16x32_bf16 v[54:57], v[98:101], v[190:193], v[54:57]
	v_mfma_f32_16x16x32_bf16 v[38:41], v[98:101], v[198:201], v[38:41]
	v_mfma_f32_16x16x32_bf16 v[38:41], v[102:105], v[202:205], v[38:41]
	v_mfma_f32_16x16x32_bf16 v[46:49], v[86:89], v[202:205], v[46:49]
	v_mfma_f32_16x16x32_bf16 v[46:49], v[82:85], v[198:201], v[46:49]
	v_mfma_f32_16x16x32_bf16 v[30:33], v[82:85], v[206:209], v[30:33]
	v_mfma_f32_16x16x32_bf16 v[30:33], v[86:89], v[210:213], v[30:33]
	v_mfma_f32_16x16x32_bf16 v[22:25], v[102:105], v[210:213], v[22:25]
	v_mfma_f32_16x16x32_bf16 v[22:25], v[98:101], v[206:209], v[22:25]
	v_mfma_f32_16x16x32_bf16 v[6:9], v[98:101], v[214:217], v[6:9]
	v_mfma_f32_16x16x32_bf16 v[6:9], v[102:105], v[218:221], v[6:9]
	v_mfma_f32_16x16x32_bf16 v[14:17], v[86:89], v[218:221], v[14:17]
	v_mfma_f32_16x16x32_bf16 v[14:17], v[82:85], v[214:217], v[14:17]
	v_mfma_f32_16x16x32_bf16 v[58:61], v[150:153], v[190:193], v[58:61]
	v_mfma_f32_16x16x32_bf16 v[58:61], v[154:157], v[194:197], v[58:61]
	v_mfma_f32_16x16x32_bf16 v[50:53], v[186:189], v[194:197], v[50:53]
	v_mfma_f32_16x16x32_bf16 v[50:53], v[182:185], v[190:193], v[50:53]
	v_mfma_f32_16x16x32_bf16 v[34:37], v[182:185], v[198:201], v[34:37]
	v_mfma_f32_16x16x32_bf16 v[34:37], v[186:189], v[202:205], v[34:37]
	v_mfma_f32_16x16x32_bf16 v[42:45], v[154:157], v[202:205], v[42:45]
	v_mfma_f32_16x16x32_bf16 v[42:45], v[150:153], v[198:201], v[42:45]
	v_mfma_f32_16x16x32_bf16 v[26:29], v[150:153], v[206:209], v[26:29]
	v_mfma_f32_16x16x32_bf16 v[26:29], v[154:157], v[210:213], v[26:29]
	v_mfma_f32_16x16x32_bf16 v[18:21], v[186:189], v[210:213], v[18:21]
	v_mfma_f32_16x16x32_bf16 v[18:21], v[182:185], v[206:209], v[18:21]
	v_mfma_f32_16x16x32_bf16 v[2:5], v[182:185], v[214:217], v[2:5]
	v_mfma_f32_16x16x32_bf16 v[2:5], v[186:189], v[218:221], v[2:5]
	v_mfma_f32_16x16x32_bf16 v[10:13], v[154:157], v[218:221], v[10:13]
	v_mfma_f32_16x16x32_bf16 v[10:13], v[150:153], v[214:217], v[10:13]
	s_barrier
	s_setprio 0
	s_add_i32 s63, s63, 2
	s_addk_i32 s61, 0x100
	s_addk_i32 s62, 0x100
	.p2align	6
